# removed compiler-inserted vmcnt ladders at GEMM unit starts; write-through (sc1) prologue stores; first A-tile DMA issued behind the ssq loads
# speedup vs baseline: 1.0023x; 1.0023x over previous
.LBB0_39:
	ds_read2_b32 v[90:91], v47 offset0:33 offset1:41
	ds_read2_b32 v[92:93], v47 offset1:8
	ds_read2_b32 v[94:95], v47 offset0:66 offset1:74
	ds_read2_b32 v[96:97], v47 offset0:99 offset1:107
	ds_read2_b32 v[100:101], v47 offset0:132 offset1:140
	ds_read2_b32 v[102:103], v47 offset0:165 offset1:173
	ds_read2_b32 v[104:105], v47 offset0:198 offset1:206
	ds_read2_b32 v[106:107], v47 offset0:231 offset1:239
	s_waitcnt vmcnt(0)
	v_mov_b32_e32 v98, v38
	v_mov_b32_e32 v99, v40
	v_mov_b32_e32 v40, v39
	s_waitcnt lgkmcnt(7)
	v_mov_b32_e32 v38, v90
	s_waitcnt lgkmcnt(4)
	v_mov_b32_e32 v39, v96
	v_mov_b32_e32 v108, v34
	v_mov_b32_e32 v109, v36
	v_mov_b32_e32 v36, v35
	s_waitcnt lgkmcnt(2)
	v_mov_b32_e32 v34, v102
	s_waitcnt lgkmcnt(0)
	v_mov_b32_e32 v35, v106
	v_mov_b32_e32 v86, v92
	v_mov_b32_e32 v87, v94
	v_pk_mul_f32 v[38:39], v[40:41], v[38:39]
	v_mov_b32_e32 v88, v100
	v_mov_b32_e32 v89, v104
	v_pk_mul_f32 v[34:35], v[36:37], v[34:35]
	v_pk_mul_f32 v[86:87], v[98:99], v[86:87]
	v_pk_mul_f32 v[88:89], v[108:109], v[88:89]
	v_bfe_u32 v90, v34, 16, 1
	v_bfe_u32 v92, v39, 16, 1
	v_bfe_u32 v94, v38, 16, 1
	v_bfe_u32 v85, v35, 16, 1
	v_add3_u32 v38, v38, v94, s62
	v_add3_u32 v39, v39, v92, s62
	v_add3_u32 v34, v34, v90, s62
	v_bfe_u32 v90, v87, 16, 1
	v_bfe_u32 v92, v88, 16, 1
	v_bfe_u32 v94, v89, 16, 1
	v_add3_u32 v35, v35, v85, s62
	v_bfe_u32 v85, v86, 16, 1
	v_add3_u32 v89, v89, v94, s62
	v_add3_u32 v88, v88, v92, s62
	v_add3_u32 v87, v87, v90, s62
	v_add3_u32 v85, v86, v85, s62
	v_lshrrev_b32_e32 v86, 16, v87
	v_lshrrev_b32_e32 v87, 16, v88
	v_lshrrev_b32_e32 v88, 16, v89
	v_and_or_b32 v89, v35, s63, v88
	v_and_or_b32 v88, v34, s63, v87
	v_add_u32_e32 v34, s41, v43
	v_mul_hi_i32_i24_e32 v35, s48, v34
	v_mul_i32_i24_e32 v34, s48, v34
	v_lshl_add_u64 v[34:35], v[34:35], 1, s[22:23]
	s_lshl_b64 s[4:5], s[50:51], 1
	v_lshrrev_b32_e32 v85, 16, v85
	v_lshl_add_u64 v[34:35], v[34:35], 0, s[4:5]
	v_and_or_b32 v87, v39, s63, v86
	v_and_or_b32 v86, v38, s63, v85
	v_lshl_add_u64 v[34:35], v[34:35], 0, v[44:45]
	v_mov_b32_e32 v96, v91
	v_mov_b32_e32 v106, v103
	global_store_dwordx4 v[34:35], v[86:89], off sc1
	v_mov_b32_e32 v94, v93
	v_pk_mul_f32 v[38:39], v[40:41], v[96:97]
	v_mov_b32_e32 v104, v101
	v_pk_mul_f32 v[88:89], v[36:37], v[106:107]
	v_pk_mul_f32 v[34:35], v[98:99], v[94:95]
	v_pk_mul_f32 v[86:87], v[108:109], v[104:105]
	v_bfe_u32 v85, v89, 16, 1
	v_bfe_u32 v91, v39, 16, 1
	v_bfe_u32 v90, v88, 16, 1
	v_bfe_u32 v92, v38, 16, 1
	v_add3_u32 v39, v39, v91, s62
	v_add3_u32 v85, v89, v85, s62
	v_bfe_u32 v89, v34, 16, 1
	v_bfe_u32 v91, v86, 16, 1
	v_add3_u32 v38, v38, v92, s62
	v_add3_u32 v88, v88, v90, s62
	v_bfe_u32 v90, v35, 16, 1
	v_bfe_u32 v92, v87, 16, 1
	v_add3_u32 v86, v86, v91, s62
	v_add3_u32 v34, v34, v89, s62
	v_add3_u32 v87, v87, v92, s62
	v_add3_u32 v35, v35, v90, s62
	v_lshrrev_b32_e32 v34, 16, v34
	v_lshrrev_b32_e32 v86, 16, v86
	v_lshrrev_b32_e32 v35, 16, v35
	v_lshrrev_b32_e32 v87, 16, v87
	v_and_or_b32 v88, v88, s63, v86
	v_and_or_b32 v86, v38, s63, v34
	v_add_u32_e32 v34, s41, v48
	v_and_or_b32 v89, v85, s63, v87
	v_and_or_b32 v87, v39, s63, v35
	v_mul_hi_i32_i24_e32 v35, s48, v34
	v_mul_i32_i24_e32 v34, s48, v34
	v_lshl_add_u64 v[34:35], v[34:35], 1, s[22:23]
	v_lshl_add_u64 v[34:35], v[34:35], 0, s[4:5]
	v_lshl_add_u64 v[34:35], v[34:35], 0, v[44:45]
	ds_read2_b32 v[38:39], v47 offset0:16 offset1:24
	ds_read2_b32 v[90:91], v47 offset0:82 offset1:90
	global_store_dwordx4 v[34:35], v[86:89], off sc1
	ds_read2_b32 v[34:35], v47 offset0:49 offset1:57
	ds_read2_b32 v[92:93], v47 offset0:115 offset1:123
	ds_read2_b32 v[94:95], v47 offset0:148 offset1:156
	ds_read2_b32 v[96:97], v47 offset0:214 offset1:222
	ds_read2_b32 v[100:101], v47 offset0:181 offset1:189
	ds_read2_b32 v[102:103], v47 offset0:247 offset1:255
	s_waitcnt lgkmcnt(7)
	v_mov_b32_e32 v86, v38
	s_waitcnt lgkmcnt(5)
	v_mov_b32_e32 v88, v34
	s_waitcnt lgkmcnt(4)
	v_mov_b32_e32 v89, v92
	s_waitcnt lgkmcnt(3)
	v_mov_b32_e32 v104, v94
	s_waitcnt lgkmcnt(2)
	v_mov_b32_e32 v105, v96
	v_mov_b32_e32 v87, v90
	v_pk_mul_f32 v[88:89], v[40:41], v[88:89]
	v_pk_mul_f32 v[104:105], v[108:109], v[104:105]
	s_waitcnt lgkmcnt(1)
	v_mov_b32_e32 v106, v100
	s_waitcnt lgkmcnt(0)
	v_mov_b32_e32 v107, v102
	v_pk_mul_f32 v[86:87], v[98:99], v[86:87]
	v_pk_mul_f32 v[106:107], v[36:37], v[106:107]
	v_bfe_u32 v85, v89, 16, 1
	v_bfe_u32 v94, v105, 16, 1
	v_bfe_u32 v34, v107, 16, 1
	v_add3_u32 v85, v89, v85, s62
	v_bfe_u32 v89, v87, 16, 1
	v_add3_u32 v94, v105, v94, s62
	v_bfe_u32 v90, v88, 16, 1
	v_add3_u32 v34, v107, v34, s62
	v_add3_u32 v87, v87, v89, s62
	v_lshrrev_b32_e32 v89, 16, v94
	v_add3_u32 v90, v88, v90, s62
	v_bfe_u32 v88, v86, 16, 1
	v_bfe_u32 v92, v104, 16, 1
	v_and_or_b32 v89, v34, s63, v89
	v_add_u32_e32 v34, s41, v49
	v_add3_u32 v92, v104, v92, s62
	v_add3_u32 v86, v86, v88, s62
	v_mul_hi_i32_i24_e32 v105, s48, v34
	v_mul_i32_i24_e32 v104, s48, v34
	v_bfe_u32 v38, v106, 16, 1
	v_lshrrev_b32_e32 v86, 16, v86
	v_lshl_add_u64 v[104:105], v[104:105], 1, s[22:23]
	v_mov_b32_e32 v102, v101
	v_add3_u32 v38, v106, v38, s62
	v_lshrrev_b32_e32 v87, 16, v87
	v_lshrrev_b32_e32 v88, 16, v92
	v_and_or_b32 v86, v90, s63, v86
	v_lshl_add_u64 v[104:105], v[104:105], 0, s[4:5]
	v_mov_b32_e32 v90, v39
	v_pk_mul_f32 v[36:37], v[36:37], v[102:103]
	v_and_or_b32 v88, v38, s63, v88
	v_and_or_b32 v87, v85, s63, v87
	v_lshl_add_u64 v[104:105], v[104:105], 0, v[44:45]
	v_pk_mul_f32 v[38:39], v[98:99], v[90:91]
	v_mov_b32_e32 v92, v35
	v_bfe_u32 v85, v37, 16, 1
	global_store_dwordx4 v[104:105], v[86:89], off sc1
	v_pk_mul_f32 v[34:35], v[40:41], v[92:93]
	v_add3_u32 v37, v37, v85, s62
	v_bfe_u32 v86, v36, 16, 1
	v_bfe_u32 v85, v38, 16, 1
	v_bfe_u32 v88, v34, 16, 1
	v_add3_u32 v36, v36, v86, s62
	v_bfe_u32 v86, v39, 16, 1
	v_add3_u32 v38, v38, v85, s62
	v_mov_b32_e32 v96, v95
	v_bfe_u32 v87, v35, 16, 1
	v_add3_u32 v34, v34, v88, s62
	v_add3_u32 v39, v39, v86, s62
	v_lshrrev_b32_e32 v38, 16, v38
	v_pk_mul_f32 v[40:41], v[108:109], v[96:97]
	v_add3_u32 v35, v35, v87, s62
	v_lshrrev_b32_e32 v39, 16, v39
	v_and_or_b32 v34, v34, s63, v38
	v_add_u32_e32 v38, s41, v50
	v_bfe_u32 v87, v40, 16, 1
	v_bfe_u32 v88, v41, 16, 1
	v_and_or_b32 v35, v35, s63, v39
	v_mul_hi_i32_i24_e32 v39, s48, v38
	v_mul_i32_i24_e32 v38, s48, v38
	v_add3_u32 v41, v41, v88, s62
	v_add3_u32 v40, v40, v87, s62
	v_lshl_add_u64 v[38:39], v[38:39], 1, s[22:23]
	v_lshrrev_b32_e32 v40, 16, v40
	v_lshrrev_b32_e32 v41, 16, v41
	v_lshl_add_u64 v[38:39], v[38:39], 0, s[4:5]
	v_and_or_b32 v37, v37, s63, v41
	v_and_or_b32 v36, v36, s63, v40
	v_lshl_add_u64 v[38:39], v[38:39], 0, v[44:45]
	global_store_dwordx4 v[38:39], v[34:37], off sc1
	s_waitcnt lgkmcnt(0)

.LBB0_83:
	ds_read2_b32 v[96:97], v47 offset0:33 offset1:41
	ds_read2_b32 v[98:99], v47 offset1:8
	ds_read2_b32 v[100:101], v47 offset0:66 offset1:74
	ds_read2_b32 v[102:103], v47 offset0:99 offset1:107
	ds_read2_b32 v[106:107], v47 offset0:132 offset1:140
	ds_read2_b32 v[108:109], v47 offset0:165 offset1:173
	ds_read2_b32 v[110:111], v47 offset0:198 offset1:206
	ds_read2_b32 v[112:113], v47 offset0:231 offset1:239
	s_waitcnt vmcnt(0)
	v_mov_b32_e32 v104, v38
	v_mov_b32_e32 v105, v40
	v_mov_b32_e32 v40, v39
	s_waitcnt lgkmcnt(7)
	v_mov_b32_e32 v38, v96
	s_waitcnt lgkmcnt(4)
	v_mov_b32_e32 v39, v102
	v_pk_mul_f32 v[38:39], v[40:41], v[38:39]
	v_mov_b32_e32 v114, v34
	v_mov_b32_e32 v115, v36
	s_waitcnt lgkmcnt(3)
	v_mov_b32_e32 v94, v106
	s_waitcnt lgkmcnt(1)
	v_mov_b32_e32 v95, v110
	v_mov_b32_e32 v93, v100
	v_pk_mul_f32 v[94:95], v[114:115], v[94:95]
	v_mov_b32_e32 v36, v35
	v_mov_b32_e32 v34, v108
	s_waitcnt lgkmcnt(0)
	v_mov_b32_e32 v35, v112
	v_bfe_u32 v100, v39, 16, 1
	v_pk_mul_f32 v[34:35], v[36:37], v[34:35]
	v_bfe_u32 v102, v38, 16, 1
	v_add3_u32 v39, v39, v100, s62
	v_bfe_u32 v100, v94, 16, 1
	v_mov_b32_e32 v92, v98
	v_bfe_u32 v98, v34, 16, 1
	v_add3_u32 v38, v38, v102, s62
	v_bfe_u32 v102, v95, 16, 1
	v_add3_u32 v94, v94, v100, s62
	v_bfe_u32 v96, v35, 16, 1
	v_add3_u32 v34, v34, v98, s62
	v_add3_u32 v95, v95, v102, s62
	v_lshrrev_b32_e32 v94, 16, v94
	v_pk_mul_f32 v[92:93], v[104:105], v[92:93]
	v_add3_u32 v35, v35, v96, s62
	v_lshrrev_b32_e32 v95, 16, v95
	v_and_or_b32 v94, v34, s63, v94
	v_add_u32_e32 v34, s41, v43
	v_bfe_u32 v96, v92, 16, 1
	v_bfe_u32 v98, v93, 16, 1
	v_and_or_b32 v95, v35, s63, v95
	v_mul_hi_i32_i24_e32 v35, s48, v34
	v_mul_i32_i24_e32 v34, s48, v34
	v_add3_u32 v93, v93, v98, s62
	v_add3_u32 v92, v92, v96, s62
	v_lshl_add_u64 v[34:35], v[34:35], 1, s[6:7]
	s_lshl_b64 s[14:15], s[50:51], 1
	v_lshrrev_b32_e32 v92, 16, v92
	v_lshrrev_b32_e32 v93, 16, v93
	v_lshl_add_u64 v[34:35], v[34:35], 0, s[14:15]
	v_and_or_b32 v93, v39, s63, v93
	v_and_or_b32 v92, v38, s63, v92
	v_lshl_add_u64 v[34:35], v[34:35], 0, v[44:45]
	v_mov_b32_e32 v102, v97
	v_mov_b32_e32 v112, v109
	global_store_dwordx4 v[34:35], v[92:95], off sc1
	v_mov_b32_e32 v100, v99
	v_pk_mul_f32 v[38:39], v[40:41], v[102:103]
	v_mov_b32_e32 v110, v107
	v_pk_mul_f32 v[94:95], v[36:37], v[112:113]
	v_pk_mul_f32 v[34:35], v[104:105], v[100:101]
	v_pk_mul_f32 v[92:93], v[114:115], v[110:111]
	v_bfe_u32 v96, v95, 16, 1
	v_bfe_u32 v98, v39, 16, 1
	v_bfe_u32 v97, v94, 16, 1
	v_bfe_u32 v99, v38, 16, 1
	v_add3_u32 v39, v39, v98, s62
	v_add3_u32 v95, v95, v96, s62
	v_bfe_u32 v96, v34, 16, 1
	v_bfe_u32 v98, v92, 16, 1
	v_add3_u32 v38, v38, v99, s62
	v_add3_u32 v94, v94, v97, s62
	v_bfe_u32 v97, v35, 16, 1
	v_bfe_u32 v99, v93, 16, 1
	v_add3_u32 v92, v92, v98, s62
	v_add3_u32 v34, v34, v96, s62
	v_add3_u32 v93, v93, v99, s62
	v_add3_u32 v35, v35, v97, s62
	v_lshrrev_b32_e32 v34, 16, v34
	v_lshrrev_b32_e32 v92, 16, v92
	v_lshrrev_b32_e32 v35, 16, v35
	v_lshrrev_b32_e32 v93, 16, v93
	v_and_or_b32 v94, v94, s63, v92
	v_and_or_b32 v92, v38, s63, v34
	v_add_u32_e32 v34, s41, v48
	v_and_or_b32 v95, v95, s63, v93
	v_and_or_b32 v93, v39, s63, v35
	v_mul_hi_i32_i24_e32 v35, s48, v34
	v_mul_i32_i24_e32 v34, s48, v34
	v_lshl_add_u64 v[34:35], v[34:35], 1, s[6:7]
	v_lshl_add_u64 v[34:35], v[34:35], 0, s[14:15]
	v_lshl_add_u64 v[34:35], v[34:35], 0, v[44:45]
	ds_read2_b32 v[38:39], v47 offset0:16 offset1:24
	ds_read2_b32 v[96:97], v47 offset0:82 offset1:90
	global_store_dwordx4 v[34:35], v[92:95], off sc1
	ds_read2_b32 v[34:35], v47 offset0:49 offset1:57
	ds_read2_b32 v[98:99], v47 offset0:115 offset1:123
	ds_read2_b32 v[100:101], v47 offset0:148 offset1:156
	ds_read2_b32 v[102:103], v47 offset0:214 offset1:222
	ds_read2_b32 v[106:107], v47 offset0:181 offset1:189
	ds_read2_b32 v[108:109], v47 offset0:247 offset1:255
	s_waitcnt lgkmcnt(7)
	v_mov_b32_e32 v92, v38
	s_waitcnt lgkmcnt(5)
	v_mov_b32_e32 v94, v34
	s_waitcnt lgkmcnt(4)
	v_mov_b32_e32 v95, v98
	s_waitcnt lgkmcnt(3)
	v_mov_b32_e32 v110, v100
	s_waitcnt lgkmcnt(2)
	v_mov_b32_e32 v111, v102
	v_mov_b32_e32 v93, v96
	v_pk_mul_f32 v[94:95], v[40:41], v[94:95]
	v_pk_mul_f32 v[110:111], v[114:115], v[110:111]
	s_waitcnt lgkmcnt(1)
	v_mov_b32_e32 v112, v106
	s_waitcnt lgkmcnt(0)
	v_mov_b32_e32 v113, v108
	v_pk_mul_f32 v[92:93], v[104:105], v[92:93]
	v_pk_mul_f32 v[112:113], v[36:37], v[112:113]
	v_bfe_u32 v96, v95, 16, 1
	v_bfe_u32 v102, v111, 16, 1
	v_bfe_u32 v34, v113, 16, 1
	v_add3_u32 v96, v95, v96, s62
	v_bfe_u32 v95, v93, 16, 1
	v_add3_u32 v102, v111, v102, s62
	v_add3_u32 v34, v113, v34, s62
	v_add3_u32 v93, v93, v95, s62
	v_lshrrev_b32_e32 v95, 16, v102
	v_bfe_u32 v98, v94, 16, 1
	v_bfe_u32 v100, v110, 16, 1
	v_and_or_b32 v95, v34, s63, v95
	v_add_u32_e32 v34, s41, v49
	v_add3_u32 v98, v94, v98, s62
	v_bfe_u32 v94, v92, 16, 1
	v_add3_u32 v100, v110, v100, s62
	v_mul_hi_i32_i24_e32 v111, s48, v34
	v_mul_i32_i24_e32 v110, s48, v34
	v_bfe_u32 v38, v112, 16, 1
	v_add3_u32 v92, v92, v94, s62
	v_lshl_add_u64 v[110:111], v[110:111], 1, s[6:7]
	v_add3_u32 v38, v112, v38, s62
	v_lshrrev_b32_e32 v92, 16, v92
	v_lshrrev_b32_e32 v93, 16, v93
	v_lshrrev_b32_e32 v94, 16, v100
	v_lshl_add_u64 v[110:111], v[110:111], 0, s[14:15]
	v_mov_b32_e32 v108, v107
	v_and_or_b32 v94, v38, s63, v94
	v_and_or_b32 v93, v96, s63, v93
	v_and_or_b32 v92, v98, s63, v92
	v_lshl_add_u64 v[110:111], v[110:111], 0, v[44:45]
	v_mov_b32_e32 v96, v39
	v_pk_mul_f32 v[36:37], v[36:37], v[108:109]
	global_store_dwordx4 v[110:111], v[92:95], off sc1
	v_pk_mul_f32 v[38:39], v[104:105], v[96:97]
	v_mov_b32_e32 v98, v35
	v_bfe_u32 v92, v37, 16, 1
	v_pk_mul_f32 v[34:35], v[40:41], v[98:99]
	v_bfe_u32 v93, v36, 16, 1
	v_add3_u32 v37, v37, v92, s62
	v_bfe_u32 v92, v38, 16, 1
	v_bfe_u32 v95, v34, 16, 1
	v_add3_u32 v36, v36, v93, s62
	v_bfe_u32 v93, v39, 16, 1
	v_add3_u32 v38, v38, v92, s62
	v_mov_b32_e32 v102, v101
	v_bfe_u32 v94, v35, 16, 1
	v_add3_u32 v34, v34, v95, s62
	v_add3_u32 v39, v39, v93, s62
	v_lshrrev_b32_e32 v38, 16, v38
	v_pk_mul_f32 v[40:41], v[114:115], v[102:103]
	v_add3_u32 v35, v35, v94, s62
	v_lshrrev_b32_e32 v39, 16, v39
	v_and_or_b32 v34, v34, s63, v38
	v_add_u32_e32 v38, s41, v50
	v_bfe_u32 v94, v40, 16, 1
	v_bfe_u32 v95, v41, 16, 1
	v_and_or_b32 v35, v35, s63, v39
	v_mul_hi_i32_i24_e32 v39, s48, v38
	v_mul_i32_i24_e32 v38, s48, v38
	v_add3_u32 v41, v41, v95, s62
	v_add3_u32 v40, v40, v94, s62
	v_lshl_add_u64 v[38:39], v[38:39], 1, s[6:7]
	v_lshrrev_b32_e32 v40, 16, v40
	v_lshrrev_b32_e32 v41, 16, v41
	v_lshl_add_u64 v[38:39], v[38:39], 0, s[14:15]
	v_and_or_b32 v37, v37, s63, v41
	v_and_or_b32 v36, v36, s63, v40
	v_lshl_add_u64 v[38:39], v[38:39], 0, v[44:45]
	global_store_dwordx4 v[38:39], v[34:37], off sc1
	s_waitcnt lgkmcnt(0)
	s_and_b64 vcc, exec, s[4:5]
	s_mov_b64 s[20:21], -1
	s_cbranch_vccnz .LBB0_40
	s_add_i32 s59, s58, s59
	s_add_i32 s64, s64, s58
	s_add_i32 s6, s59, 0xffffef80
	s_cmpk_lt_i32 s6, 0x1700
	s_cselect_b64 s[4:5], -1, 0
	s_cmpk_gt_i32 s6, 0x16ff
	s_cselect_b64 s[20:21], -1, 0
	s_and_b64 vcc, exec, s[20:21]
	s_cbranch_vccnz .LBB0_104
	s_cmpk_lt_i32 s6, 0xb00
	s_mov_b32 s13, s64
	s_cbranch_scc1 .LBB0_88
	s_cmpk_gt_u32 s6, 0x107f
	s_mov_b32 s13, s59
	s_cbranch_scc1 .LBB0_88
	s_add_i32 s13, s64, 0xb00

.LBB0_132:
	s_waitcnt vmcnt(15)
	v_add_co_u32_e32 v18, vcc, 0xffffd000, v54
	s_waitcnt vmcnt(12)
	s_nop 0
	v_addc_co_u32_e32 v19, vcc, -1, v55, vcc
	global_load_dwordx4 v[70:73], v[18:19], off offset:-3072 nt
	global_load_dwordx4 v[74:77], v[18:19], off offset:-2048 nt
	global_load_dwordx4 v[78:81], v[18:19], off offset:-1024 nt
	global_load_dwordx4 v[82:85], v[18:19], off nt
	s_waitcnt lgkmcnt(0)
	global_load_dwordx4 v[14:17], v[54:55], off offset:-3072 nt
	global_load_dwordx4 v[10:13], v[54:55], off offset:-2048 nt
	global_load_dwordx4 v[6:9], v[54:55], off offset:-1024 nt
	global_load_dwordx4 v[2:5], v[54:55], off nt
	v_add_co_u32_e32 v18, vcc, 0xffffe000, v54
	s_waitcnt vmcnt(6)
	v_mul_f32_e32 v58, v75, v75
	v_addc_co_u32_e32 v19, vcc, -1, v55, vcc
	v_add_co_u32_e32 v56, vcc, 0xfffff000, v54
	global_load_dwordx4 v[46:49], v[18:19], off offset:-3072 nt
	global_load_dwordx4 v[42:45], v[18:19], off offset:-2048 nt
	global_load_dwordx4 v[38:41], v[18:19], off offset:-1024 nt
	global_load_dwordx4 v[34:37], v[18:19], off nt
	v_addc_co_u32_e32 v57, vcc, -1, v55, vcc
	global_load_dwordx4 v[30:33], v[56:57], off offset:-3072 nt
	global_load_dwordx4 v[26:29], v[56:57], off offset:-2048 nt
	global_load_dwordx4 v[22:25], v[56:57], off offset:-1024 nt
	global_load_dwordx4 v[18:21], v[54:55], off offset:-4096 nt
	v_mul_f32_e32 v56, v71, v71
	v_mul_f32_e32 v57, v73, v73
	v_mul_f32_e32 v59, v77, v77
	s_waitcnt vmcnt(13)
	v_mul_f32_e32 v60, v79, v79
	v_mul_f32_e32 v61, v81, v81
	v_fmac_f32_e32 v56, v70, v70
	v_fmac_f32_e32 v57, v72, v72
	v_fmac_f32_e32 v58, v74, v74
	v_fmac_f32_e32 v59, v76, v76
	s_waitcnt vmcnt(12)
	v_mul_f32_e32 v69, v83, v83
	v_mul_f32_e32 v86, v85, v85
	v_fmac_f32_e32 v60, v78, v78
	v_fmac_f32_e32 v61, v80, v80
	v_add_f32_e32 v56, v56, v57
	v_add_f32_e32 v57, v58, v59
	v_fmac_f32_e32 v69, v82, v82
	v_fmac_f32_e32 v86, v84, v84
	v_add_f32_e32 v58, v60, v61
	v_add_f32_e32 v56, v56, v57
	v_add_f32_e32 v59, v69, v86
	v_add_f32_e32 v56, v56, v58
	v_add_f32_e32 v56, v56, v59
	ds_bpermute_b32 v57, v63, v56
	v_lshl_add_u64 v[58:59], s[28:29], 0, v[52:53]
	v_add_co_u32_e32 v60, vcc, s13, v58
	s_waitcnt lgkmcnt(0)
	v_add_f32_e32 v56, v56, v57
	ds_bpermute_b32 v57, v64, v56
	v_addc_co_u32_e32 v61, vcc, 0, v59, vcc
	s_waitcnt lgkmcnt(0)
	v_add_f32_e32 v56, v56, v57
	ds_bpermute_b32 v57, v65, v56
	s_waitcnt lgkmcnt(0)
	v_add_f32_e32 v69, v56, v57
	ds_bpermute_b32 v86, v66, v69
	v_cvt_pk_bf16_f32 v56, v70, v71
	v_cvt_pk_bf16_f32 v70, v74, v75
	v_cvt_pk_bf16_f32 v57, v72, v73
	v_cvt_pk_bf16_f32 v71, v76, v77
	s_waitcnt lgkmcnt(0)
	v_add_f32_e32 v69, v69, v86
	ds_bpermute_b32 v74, v67, v69
	global_store_dwordx2 v[60:61], v[56:57], off sc1
	global_store_dwordx2 v[60:61], v[70:71], off offset:512 sc1
	v_cvt_pk_bf16_f32 v56, v82, v83
	v_cvt_pk_bf16_f32 v57, v84, v85
	v_cvt_pk_bf16_f32 v72, v78, v79
	s_waitcnt lgkmcnt(0)
	v_add_f32_e32 v69, v69, v74
	ds_bpermute_b32 v70, v68, v69
	v_cvt_pk_bf16_f32 v73, v80, v81
	global_store_dwordx2 v[60:61], v[56:57], off offset:1536 sc1
	v_lshl_add_u64 v[56:57], s[28:29], 0, v[50:51]
	global_store_dwordx2 v[60:61], v[72:73], off offset:1024 sc1
	s_and_saveexec_b64 s[22:23], s[6:7]
	s_cbranch_execz .LBB0_134
	s_waitcnt lgkmcnt(0)
	v_add_f32_e32 v69, v69, v70
	v_add_co_u32_e32 v70, vcc, 0xb200000, v56
	v_cndmask_b32_e64 v69, 0, v69, s[4:5]
	s_nop 0
	v_addc_co_u32_e32 v71, vcc, 0, v57, vcc
	global_store_dword v[70:71], v69, off sc1
.LBB0_134:
	s_or_b64 exec, exec, s[22:23]
	s_waitcnt vmcnt(11)
	v_mul_f32_e32 v69, v47, v47
	s_waitcnt lgkmcnt(0)
	v_mul_f32_e32 v70, v49, v49
	v_fmac_f32_e32 v69, v46, v46
	v_fmac_f32_e32 v70, v48, v48
	v_add_f32_e32 v69, v69, v70
	s_waitcnt vmcnt(10)
	v_mul_f32_e32 v70, v43, v43
	v_mul_f32_e32 v71, v45, v45
	v_fmac_f32_e32 v70, v42, v42
	v_fmac_f32_e32 v71, v44, v44
	v_add_f32_e32 v70, v70, v71
	v_add_f32_e32 v69, v69, v70
	s_waitcnt vmcnt(9)
	v_mul_f32_e32 v70, v39, v39
	v_mul_f32_e32 v71, v41, v41
	v_fmac_f32_e32 v70, v38, v38
	v_fmac_f32_e32 v71, v40, v40
	v_add_f32_e32 v70, v70, v71
	v_add_f32_e32 v69, v69, v70
	s_waitcnt vmcnt(8)
	v_mul_f32_e32 v70, v35, v35
	v_mul_f32_e32 v71, v37, v37
	v_fmac_f32_e32 v70, v34, v34
	v_fmac_f32_e32 v71, v36, v36
	v_add_f32_e32 v70, v70, v71
	v_add_f32_e32 v69, v69, v70
	ds_bpermute_b32 v70, v63, v69
	v_cvt_pk_bf16_f32 v46, v46, v47
	v_cvt_pk_bf16_f32 v47, v48, v49
	global_store_dwordx2 v[60:61], v[46:47], off offset:2048 sc1
	v_cvt_pk_bf16_f32 v42, v42, v43
	s_waitcnt lgkmcnt(0)
	v_add_f32_e32 v69, v69, v70
	ds_bpermute_b32 v70, v64, v69
	v_cvt_pk_bf16_f32 v43, v44, v45
	v_cvt_pk_bf16_f32 v38, v38, v39
	v_cvt_pk_bf16_f32 v39, v40, v41
	v_cvt_pk_bf16_f32 v34, v34, v35
	s_waitcnt lgkmcnt(0)
	v_add_f32_e32 v69, v69, v70
	ds_bpermute_b32 v70, v65, v69
	v_cvt_pk_bf16_f32 v35, v36, v37
	global_store_dwordx2 v[60:61], v[42:43], off offset:2560 sc1
	global_store_dwordx2 v[60:61], v[38:39], off offset:3072 sc1
	global_store_dwordx2 v[60:61], v[34:35], off offset:3584 sc1
	s_waitcnt lgkmcnt(0)
	v_add_f32_e32 v69, v69, v70
	ds_bpermute_b32 v70, v66, v69
	s_waitcnt lgkmcnt(0)
	v_add_f32_e32 v69, v69, v70
	ds_bpermute_b32 v70, v67, v69
	s_waitcnt lgkmcnt(0)
	v_add_f32_e32 v46, v69, v70
	ds_bpermute_b32 v47, v68, v46
	s_and_saveexec_b64 s[22:23], s[6:7]
	s_cbranch_execz .LBB0_136
	s_waitcnt lgkmcnt(0)
	v_add_f32_e32 v34, v46, v47
	v_cndmask_b32_e64 v36, 0, v34, s[4:5]
	v_add_co_u32_e32 v34, vcc, 0xb200000, v56
	s_nop 1
	v_addc_co_u32_e32 v35, vcc, 0, v57, vcc
	global_store_dword v[34:35], v36, off offset:64 sc1
.LBB0_136:
	s_or_b64 exec, exec, s[22:23]
	s_waitcnt vmcnt(11)
	v_mul_f32_e32 v34, v31, v31
	v_mul_f32_e32 v35, v33, v33
	v_fmac_f32_e32 v34, v30, v30
	v_fmac_f32_e32 v35, v32, v32
	v_add_f32_e32 v34, v34, v35
	s_waitcnt vmcnt(10)
	v_mul_f32_e32 v35, v27, v27
	v_mul_f32_e32 v36, v29, v29
	v_fmac_f32_e32 v35, v26, v26
	v_fmac_f32_e32 v36, v28, v28
	v_add_f32_e32 v35, v35, v36
	v_add_f32_e32 v34, v34, v35
	s_waitcnt vmcnt(9)
	v_mul_f32_e32 v35, v23, v23
	v_mul_f32_e32 v36, v25, v25
	v_fmac_f32_e32 v35, v22, v22
	v_fmac_f32_e32 v36, v24, v24
	v_add_f32_e32 v35, v35, v36
	v_add_f32_e32 v34, v34, v35
	s_waitcnt vmcnt(8)
	v_mul_f32_e32 v35, v19, v19
	v_mul_f32_e32 v36, v21, v21
	v_fmac_f32_e32 v35, v18, v18
	v_fmac_f32_e32 v36, v20, v20
	v_add_f32_e32 v35, v35, v36
	v_add_f32_e32 v34, v34, v35
	ds_bpermute_b32 v35, v63, v34
	v_cvt_pk_bf16_f32 v26, v26, v27
	v_cvt_pk_bf16_f32 v27, v28, v29
	v_cvt_pk_bf16_f32 v22, v22, v23
	v_cvt_pk_bf16_f32 v23, v24, v25
	s_waitcnt lgkmcnt(0)
	v_add_f32_e32 v34, v34, v35
	ds_bpermute_b32 v35, v64, v34
	v_cvt_pk_bf16_f32 v18, v18, v19
	v_cvt_pk_bf16_f32 v19, v20, v21
	s_waitcnt lgkmcnt(0)
	v_add_f32_e32 v34, v34, v35
	ds_bpermute_b32 v35, v65, v34
	s_waitcnt lgkmcnt(0)
	v_add_f32_e32 v34, v34, v35
	ds_bpermute_b32 v35, v66, v34
	s_waitcnt lgkmcnt(0)
	v_add_f32_e32 v36, v34, v35
	ds_bpermute_b32 v37, v67, v36
	v_cvt_pk_bf16_f32 v35, v32, v33
	v_cvt_pk_bf16_f32 v34, v30, v31
	v_add_co_u32_e32 v30, vcc, s15, v58
	s_waitcnt lgkmcnt(0)
	v_add_f32_e32 v32, v36, v37
	ds_bpermute_b32 v33, v68, v32
	v_addc_co_u32_e32 v31, vcc, 0, v59, vcc
	global_store_dwordx2 v[30:31], v[34:35], off sc1
	global_store_dwordx2 v[30:31], v[26:27], off offset:512 sc1
	global_store_dwordx2 v[30:31], v[22:23], off offset:1024 sc1
	global_store_dwordx2 v[30:31], v[18:19], off offset:1536 sc1
	s_and_saveexec_b64 s[22:23], s[6:7]
	s_cbranch_execz .LBB0_138
	s_waitcnt lgkmcnt(0)
	v_add_f32_e32 v18, v32, v33
	v_cndmask_b32_e64 v20, 0, v18, s[4:5]
	v_add_co_u32_e32 v18, vcc, 0xb200000, v56
	s_nop 1
	v_addc_co_u32_e32 v19, vcc, 0, v57, vcc
	global_store_dword v[18:19], v20, off offset:128 sc1
.LBB0_138:
	s_or_b64 exec, exec, s[22:23]
	v_mul_f32_e32 v18, v15, v15
	v_mul_f32_e32 v19, v17, v17
	v_fmac_f32_e32 v18, v14, v14
	v_fmac_f32_e32 v19, v16, v16
	v_add_f32_e32 v18, v18, v19
	v_mul_f32_e32 v19, v11, v11
	v_mul_f32_e32 v20, v13, v13
	v_fmac_f32_e32 v19, v10, v10
	v_fmac_f32_e32 v20, v12, v12
	v_add_f32_e32 v19, v19, v20
	v_add_f32_e32 v18, v18, v19
	v_mul_f32_e32 v19, v7, v7
	v_mul_f32_e32 v20, v9, v9
	v_fmac_f32_e32 v19, v6, v6
	v_fmac_f32_e32 v20, v8, v8
	v_add_f32_e32 v19, v19, v20
	v_add_f32_e32 v18, v18, v19
	v_mul_f32_e32 v19, v3, v3
	v_mul_f32_e32 v20, v5, v5
	v_fmac_f32_e32 v19, v2, v2
	v_fmac_f32_e32 v20, v4, v4
	v_add_f32_e32 v19, v19, v20
	v_add_f32_e32 v18, v18, v19
	ds_bpermute_b32 v19, v63, v18
	v_cvt_pk_bf16_f32 v14, v14, v15
	v_cvt_pk_bf16_f32 v15, v16, v17
	global_store_dwordx2 v[30:31], v[14:15], off offset:2048 sc1
	v_cvt_pk_bf16_f32 v10, v10, v11
	s_waitcnt lgkmcnt(0)
	v_add_f32_e32 v18, v18, v19
	ds_bpermute_b32 v19, v64, v18
	v_cvt_pk_bf16_f32 v11, v12, v13
	v_cvt_pk_bf16_f32 v6, v6, v7
	v_cvt_pk_bf16_f32 v7, v8, v9
	v_cvt_pk_bf16_f32 v2, v2, v3
	s_waitcnt lgkmcnt(0)
	v_add_f32_e32 v18, v18, v19
	ds_bpermute_b32 v19, v65, v18
	v_cvt_pk_bf16_f32 v3, v4, v5
	global_store_dwordx2 v[30:31], v[10:11], off offset:2560 sc1
	global_store_dwordx2 v[30:31], v[6:7], off offset:3072 sc1
	global_store_dwordx2 v[30:31], v[2:3], off offset:3584 sc1
	s_waitcnt lgkmcnt(0)
	v_add_f32_e32 v18, v18, v19
	ds_bpermute_b32 v19, v66, v18
	s_waitcnt lgkmcnt(0)
	v_add_f32_e32 v18, v18, v19
	ds_bpermute_b32 v19, v67, v18
	s_waitcnt lgkmcnt(0)
	v_add_f32_e32 v14, v18, v19
	ds_bpermute_b32 v15, v68, v14
	s_and_saveexec_b64 s[22:23], s[6:7]
	s_cbranch_execz .LBB0_131
	s_waitcnt lgkmcnt(0)
	v_add_f32_e32 v2, v14, v15
	v_cndmask_b32_e64 v4, 0, v2, s[4:5]
	v_add_co_u32_e32 v2, vcc, 0xb200000, v56
	s_nop 1
	v_addc_co_u32_e32 v3, vcc, 0, v57, vcc
	global_store_dword v[2:3], v4, off offset:192 sc1
	s_branch .LBB0_131

.LBB0_377:
	s_or_b64 exec, exec, s[72:73]
	s_add_u32 s6, s68, 0xb300000
	v_mov_b32_e32 v2, v0
	s_addc_u32 s7, s69, 0
	s_barrier
	s_lshl_b32 s9, s17, 14
	v_ashrrev_i32_e32 v4, 1, v2
	v_ashrrev_i32_e32 v5, 31, v4
	s_add_u32 s18, s6, s9
	v_and_b32_e32 v11, 1, v2
	s_addc_u32 s19, s7, 0
	s_waitcnt vmcnt(18)
	v_lshlrev_b64 v[12:13], 6, v[4:5]
	v_lshl_add_u64 v[12:13], s[18:19], 0, v[12:13]
	v_lshlrev_b32_e32 v2, 5, v11
	s_waitcnt vmcnt(10)
	v_lshl_add_u64 v[20:21], v[12:13], 0, v[2:3]
	global_load_dwordx4 v[12:15], v[20:21], off sc1
	global_load_dwordx4 v[16:19], v[20:21], off offset:16 sc1
	s_waitcnt lgkmcnt(0)
	s_add_u32 s9, s66, 0x2a00000
	s_addc_u32 s18, s67, 0
	s_lshl_b32 s19, s17, 19
	s_add_u32 s66, s9, s19
	s_addc_u32 s67, s18, 0
	v_lshl_add_u32 v136, v7, 11, v8
	s_add_i32 m0, s16, 0
	s_nop 0
	global_load_lds_dwordx4 v136, s[66:67]
	s_ashr_i32 s33, s29, 8
	v_lshl_add_u32 v137, v9, 11, v10
	s_add_i32 m0, s16, 0x2000
	s_nop 0
	global_load_lds_dwordx4 v137, s[66:67]
	s_add_u32 s38, s66, 0x40000
	s_addc_u32 s39, s67, 0
	s_add_i32 m0, s16, 0x4000
	s_nop 0
	global_load_lds_dwordx4 v136, s[38:39]
	s_nop 0
	s_add_i32 m0, s16, 0x6000
	s_nop 0
	global_load_lds_dwordx4 v137, s[38:39]
	s_waitcnt vmcnt(4)
	s_nop 0
	v_add_f32_e32 v2, v12, v13
	v_add_f32_e32 v5, v14, v15
	v_add_f32_e32 v2, v2, v5
	v_add_f32_e32 v5, v16, v17
	v_add_f32_e32 v12, v18, v19
	v_add_f32_e32 v5, v5, v12
	v_and_b32_e32 v12, 64, v192
	v_add_f32_e32 v2, v2, v5
	v_xor_b32_e32 v5, 1, v192
	v_add_u32_e32 v12, 64, v12
	v_cmp_lt_i32_e32 vcc, v5, v12
	s_nop 1
	v_cndmask_b32_e32 v5, v192, v5, vcc
	v_lshlrev_b32_e32 v135, 2, v5
	ds_bpermute_b32 v5, v135, v2
	v_cmp_eq_u32_e32 vcc, 0, v11
	s_and_saveexec_b64 s[68:69], vcc
	s_cbranch_execz .LBB0_379
	s_waitcnt lgkmcnt(0)
	v_add_f32_e32 v2, v2, v5
	v_fmamk_f32 v2, v2, 0x3a800000, v254
	s_lshl_b32 s100, s17, 8
	v_rsq_f32_e32 v5, v2
	s_and_b32 s100, s100, 0x400
	s_add_i32 s100, s100, 0
	v_lshl_add_u32 v4, v4, 2, s100
	v_add_u32_e32 v4, 0x24400, v4
	ds_write2st64_b32 v4, v5, v2 offset1:8
.LBB0_379:
	s_or_b64 exec, exec, s[68:69]
	s_cmp_eq_u32 s33, 1
	s_cselect_b64 s[68:69], -1, 0
	s_cmp_lg_u32 s33, 1
	s_cbranch_scc1 .LBB0_381
	s_barrier

.LBB0_382:
	s_add_i32 s39, s33, 1
	s_mov_b32 s47, s37
	s_add_i32 s37, s39, s35
	s_mul_i32 s37, s37, s23
	s_add_i32 s37, s37, s22
	s_mov_b32 s43, s38
	s_add_i32 s38, s37, 0xffffff28
	s_cmpk_lt_i32 s38, 0x48
	s_cselect_b64 s[76:77], -1, 0
	s_cmpk_gt_i32 s38, 0x47
	s_cselect_b64 s[72:73], -1, 0
	s_cmp_lt_i32 s38, 36
	s_cselect_b32 s41, 0, 0xffffffdc
	s_cselect_b32 s44, 0, 4
	s_add_i32 s38, s41, s38
	s_and_b32 s45, s37, 3
	s_ashr_i32 s37, s38, 2
	s_or_b32 s38, s45, s44
	s_or_b32 s38, s38, s28
	s_and_b64 s[44:45], s[76:77], exec
	s_cselect_b32 s80, s38, s43
	s_cselect_b32 s44, s37, s47
	s_ashr_i32 s81, s80, 31
	s_lshl_b64 s[50:51], s[80:81], 19
	s_add_u32 s74, s9, s50
	s_addc_u32 s75, s18, s51
	s_ashr_i32 s45, s44, 31
	s_lshl_b64 s[44:45], s[44:45], 19
	s_add_u32 s78, s14, s44
	s_addc_u32 s79, s15, s45
	s_add_u32 s84, s66, 0x100
	s_addc_u32 s85, s67, 0
	v_add_u32_e32 v142, 0x10000, v140
	v_add_u32_e32 v143, 0x14000, v140
	s_add_u32 s82, s66, 0x180
	ds_read_b128 v[4:7], v142
	ds_read_b128 v[8:11], v142 offset:1024
	ds_read_b128 v[12:15], v142 offset:2048
	ds_read_b128 v[16:19], v142 offset:3072
	ds_read_b128 v[20:23], v143
	ds_read_b128 v[24:27], v143 offset:1024
	ds_read_b128 v[28:31], v143 offset:2048
	ds_read_b128 v[32:35], v143 offset:3072
	s_addc_u32 s83, s67, 0
	s_and_b64 s[44:45], s[76:77], exec
	s_cselect_b32 s43, s75, s67
	s_cselect_b32 s44, s74, s66
	s_add_u32 s50, s12, 0x100
	s_addc_u32 s51, s13, 0
	s_and_b64 s[52:53], s[76:77], exec
	s_mov_b32 s41, 2
	s_cselect_b32 s45, s79, s13
	s_cselect_b32 s47, s78, s12
	ds_read_b128 v[36:39], v141
	ds_read_b128 v[40:43], v141 offset:1024
	ds_read_b128 v[44:47], v141 offset:2048
	ds_read_b128 v[48:51], v141 offset:3072
	ds_read_b128 v[52:55], v141 offset:4096
	ds_read_b128 v[56:59], v141 offset:5120
	ds_read_b128 v[60:63], v141 offset:6144
	ds_read_b128 v[64:67], v141 offset:7168
	s_add_u32 s52, s66, 0x40080
	s_addc_u32 s53, s67, 0
	s_add_i32 m0, s16, 0xc000
	s_nop 0
	global_load_lds_dwordx4 v136, s[52:53]
	s_nop 0
	s_add_i32 m0, s16, 0xe000
	s_nop 0
	global_load_lds_dwordx4 v137, s[52:53]
	s_waitcnt vmcnt(8)
	s_waitcnt lgkmcnt(0)
	s_barrier
	s_setprio 1
	s_waitcnt lgkmcnt(7)
	v_mfma_f32_16x16x32_bf16 v[68:71], v[4:7], v[36:39], 0
	v_mfma_f32_16x16x32_bf16 v[72:75], v[12:15], v[36:39], 0
	s_waitcnt lgkmcnt(5)
	v_mfma_f32_16x16x32_bf16 v[76:79], v[4:7], v[44:47], 0
	v_mfma_f32_16x16x32_bf16 v[80:83], v[12:15], v[44:47], 0
	s_waitcnt lgkmcnt(3)
	v_mfma_f32_16x16x32_bf16 v[84:87], v[4:7], v[52:55], 0
	v_mfma_f32_16x16x32_bf16 v[88:91], v[12:15], v[52:55], 0
	s_waitcnt lgkmcnt(1)
	v_mfma_f32_16x16x32_bf16 v[92:95], v[4:7], v[60:63], 0
	v_mfma_f32_16x16x32_bf16 v[96:99], v[12:15], v[60:63], 0
	v_mfma_f32_16x16x32_bf16 v[68:71], v[8:11], v[40:43], v[68:71]
	v_mfma_f32_16x16x32_bf16 v[72:75], v[16:19], v[40:43], v[72:75]
	v_mfma_f32_16x16x32_bf16 v[76:79], v[8:11], v[48:51], v[76:79]
	v_mfma_f32_16x16x32_bf16 v[80:83], v[16:19], v[48:51], v[80:83]
	v_mfma_f32_16x16x32_bf16 v[84:87], v[8:11], v[56:59], v[84:87]
	v_mfma_f32_16x16x32_bf16 v[88:91], v[16:19], v[56:59], v[88:91]
	s_waitcnt lgkmcnt(0)
	v_mfma_f32_16x16x32_bf16 v[92:95], v[8:11], v[64:67], v[92:95]
	v_mfma_f32_16x16x32_bf16 v[100:103], v[16:19], v[64:67], v[96:99]
	s_setprio 0
	s_setprio 1
	v_mfma_f32_16x16x32_bf16 v[96:99], v[20:23], v[36:39], 0
	v_mfma_f32_16x16x32_bf16 v[36:39], v[28:31], v[36:39], 0
	v_mfma_f32_16x16x32_bf16 v[108:111], v[24:27], v[40:43], v[96:99]
	v_mfma_f32_16x16x32_bf16 v[36:39], v[32:35], v[40:43], v[36:39]
	v_mfma_f32_16x16x32_bf16 v[40:43], v[20:23], v[44:47], 0
	v_mfma_f32_16x16x32_bf16 v[44:47], v[28:31], v[44:47], 0
	v_mfma_f32_16x16x32_bf16 v[40:43], v[24:27], v[48:51], v[40:43]
	v_mfma_f32_16x16x32_bf16 v[44:47], v[32:35], v[48:51], v[44:47]
	v_mfma_f32_16x16x32_bf16 v[48:51], v[20:23], v[52:55], 0
	v_mfma_f32_16x16x32_bf16 v[52:55], v[28:31], v[52:55], 0
	v_mfma_f32_16x16x32_bf16 v[48:51], v[24:27], v[56:59], v[48:51]
	v_mfma_f32_16x16x32_bf16 v[52:55], v[32:35], v[56:59], v[52:55]
	v_mfma_f32_16x16x32_bf16 v[56:59], v[20:23], v[60:63], 0
	v_mfma_f32_16x16x32_bf16 v[146:149], v[24:27], v[64:67], v[56:59]
	v_mfma_f32_16x16x32_bf16 v[56:59], v[28:31], v[60:63], 0
	v_mfma_f32_16x16x32_bf16 v[150:153], v[32:35], v[64:67], v[56:59]
	s_setprio 0
	s_barrier
	s_nop 4
	ds_read_b128 v[56:59], v141 offset:16384
	ds_read_b128 v[60:63], v141 offset:17408
	ds_read_b128 v[64:67], v141 offset:18432
	ds_read_b128 v[96:99], v141 offset:19456
	ds_read_b128 v[104:107], v141 offset:20480
	ds_read_b128 v[112:115], v141 offset:21504
	ds_read_b128 v[116:119], v141 offset:22528
	ds_read_b128 v[120:123], v141 offset:23552
	s_add_i32 m0, s16, 0x10000
	s_nop 0
	global_load_lds_dwordx4 v1, s[50:51]
	s_nop 0
	s_add_i32 m0, s16, 0x12000
	s_nop 0
	global_load_lds_dwordx4 v134, s[50:51]
	s_add_u32 s50, s12, 0x40100
	s_addc_u32 s51, s13, 0
	s_add_i32 m0, s16, 0x14000
	s_nop 0
	global_load_lds_dwordx4 v1, s[50:51]
	s_nop 0
	s_add_i32 m0, s16, 0x16000
	s_nop 0
	global_load_lds_dwordx4 v134, s[50:51]
	s_nop 0
	s_add_i32 m0, s16, 0
	s_nop 0
	global_load_lds_dwordx4 v136, s[84:85]
	s_nop 0
	s_add_i32 m0, s16, 0x2000
	s_nop 0
	global_load_lds_dwordx4 v137, s[84:85]
	s_waitcnt vmcnt(8)
	s_waitcnt lgkmcnt(0)
	s_barrier
	s_setprio 1
	s_waitcnt lgkmcnt(7)
	v_mfma_f32_16x16x32_bf16 v[124:127], v[4:7], v[56:59], 0
	s_waitcnt lgkmcnt(6)
	v_mfma_f32_16x16x32_bf16 v[154:157], v[8:11], v[60:63], v[124:127]
	v_mfma_f32_16x16x32_bf16 v[124:127], v[12:15], v[56:59], 0
	v_mfma_f32_16x16x32_bf16 v[158:161], v[16:19], v[60:63], v[124:127]
	s_waitcnt lgkmcnt(5)
	v_mfma_f32_16x16x32_bf16 v[124:127], v[4:7], v[64:67], 0
	s_waitcnt lgkmcnt(4)
	v_mfma_f32_16x16x32_bf16 v[162:165], v[8:11], v[96:99], v[124:127]
	v_mfma_f32_16x16x32_bf16 v[124:127], v[12:15], v[64:67], 0
	v_mfma_f32_16x16x32_bf16 v[166:169], v[16:19], v[96:99], v[124:127]
	s_waitcnt lgkmcnt(3)
	v_mfma_f32_16x16x32_bf16 v[124:127], v[4:7], v[104:107], 0
	s_waitcnt lgkmcnt(1)
	v_mfma_f32_16x16x32_bf16 v[4:7], v[4:7], v[116:119], 0
	v_mfma_f32_16x16x32_bf16 v[172:175], v[8:11], v[112:115], v[124:127]
	s_waitcnt lgkmcnt(0)
	v_mfma_f32_16x16x32_bf16 v[4:7], v[8:11], v[120:123], v[4:7]
	v_mfma_f32_16x16x32_bf16 v[8:11], v[12:15], v[116:119], 0
	v_mfma_f32_16x16x32_bf16 v[124:127], v[12:15], v[104:107], 0
	v_mfma_f32_16x16x32_bf16 v[8:11], v[16:19], v[120:123], v[8:11]
	v_mfma_f32_16x16x32_bf16 v[176:179], v[16:19], v[112:115], v[124:127]
	s_setprio 0
	s_setprio 1
	v_mfma_f32_16x16x32_bf16 v[16:19], v[28:31], v[56:59], 0
	v_mfma_f32_16x16x32_bf16 v[180:183], v[32:35], v[60:63], v[16:19]
	v_mfma_f32_16x16x32_bf16 v[16:19], v[20:23], v[64:67], 0
	v_mfma_f32_16x16x32_bf16 v[184:187], v[24:27], v[96:99], v[16:19]
	v_mfma_f32_16x16x32_bf16 v[16:19], v[28:31], v[64:67], 0
	v_mfma_f32_16x16x32_bf16 v[188:191], v[32:35], v[96:99], v[16:19]
	v_mfma_f32_16x16x32_bf16 v[16:19], v[20:23], v[104:107], 0
	v_mfma_f32_16x16x32_bf16 v[196:199], v[24:27], v[112:115], v[16:19]
	v_mfma_f32_16x16x32_bf16 v[16:19], v[28:31], v[104:107], 0
	v_mfma_f32_16x16x32_bf16 v[12:15], v[20:23], v[56:59], 0
	v_mfma_f32_16x16x32_bf16 v[200:203], v[32:35], v[112:115], v[16:19]
	v_mfma_f32_16x16x32_bf16 v[16:19], v[20:23], v[116:119], 0
	v_mfma_f32_16x16x32_bf16 v[12:15], v[24:27], v[60:63], v[12:15]
	v_mfma_f32_16x16x32_bf16 v[204:207], v[24:27], v[120:123], v[16:19]
	v_mfma_f32_16x16x32_bf16 v[16:19], v[28:31], v[116:119], 0
	v_mfma_f32_16x16x32_bf16 v[208:211], v[32:35], v[120:123], v[16:19]
	s_setprio 0
	s_barrier
	v_add_u32_e32 v144, 0x18000, v140
	v_add_u32_e32 v145, 0x1c000, v140
	s_nop 2
	ds_read_b128 v[16:19], v144
	ds_read_b128 v[20:23], v144 offset:1024
	ds_read_b128 v[28:31], v144 offset:2048
	ds_read_b128 v[212:215], v144 offset:3072
	ds_read_b128 v[216:219], v145
	ds_read_b128 v[220:223], v145 offset:1024
	ds_read_b128 v[224:227], v145 offset:2048
	ds_read_b128 v[228:231], v145 offset:3072
	ds_read_b128 v[24:27], v141 offset:32768
	ds_read_b128 v[32:35], v141 offset:33792
	ds_read_b128 v[60:63], v141 offset:34816
	ds_read_b128 v[232:235], v141 offset:35840
	ds_read_b128 v[236:239], v141 offset:36864
	ds_read_b128 v[240:243], v141 offset:37888
	ds_read_b128 v[244:247], v141 offset:38912
	ds_read_b128 v[248:251], v141 offset:39936
	s_add_u32 s50, s66, 0x40100
	s_addc_u32 s51, s67, 0
	s_add_i32 m0, s16, 0x4000
	s_nop 0
	global_load_lds_dwordx4 v136, s[50:51]
	s_nop 0
	s_add_i32 m0, s16, 0x6000
	s_nop 0
	global_load_lds_dwordx4 v137, s[50:51]
	s_waitcnt vmcnt(8)
	s_waitcnt lgkmcnt(0)
	s_barrier
	s_setprio 1
	s_waitcnt lgkmcnt(7)
	v_mfma_f32_16x16x32_bf16 v[56:59], v[16:19], v[24:27], v[68:71]
	s_waitcnt lgkmcnt(6)
	v_mfma_f32_16x16x32_bf16 v[128:131], v[20:23], v[32:35], v[56:59]
	v_mfma_f32_16x16x32_bf16 v[56:59], v[28:31], v[24:27], v[72:75]
	v_mfma_f32_16x16x32_bf16 v[120:123], v[212:215], v[32:35], v[56:59]
	s_waitcnt lgkmcnt(5)
	v_mfma_f32_16x16x32_bf16 v[56:59], v[16:19], v[60:63], v[76:79]
	s_waitcnt lgkmcnt(4)
	v_mfma_f32_16x16x32_bf16 v[112:115], v[20:23], v[232:235], v[56:59]
	v_mfma_f32_16x16x32_bf16 v[56:59], v[28:31], v[60:63], v[80:83]
	v_mfma_f32_16x16x32_bf16 v[104:107], v[212:215], v[232:235], v[56:59]
	s_waitcnt lgkmcnt(3)
	v_mfma_f32_16x16x32_bf16 v[56:59], v[16:19], v[236:239], v[84:87]
	s_waitcnt lgkmcnt(2)
	v_mfma_f32_16x16x32_bf16 v[96:99], v[20:23], v[240:243], v[56:59]
	v_mfma_f32_16x16x32_bf16 v[56:59], v[28:31], v[236:239], v[88:91]
	v_mfma_f32_16x16x32_bf16 v[88:91], v[212:215], v[240:243], v[56:59]
	s_waitcnt lgkmcnt(1)
	v_mfma_f32_16x16x32_bf16 v[56:59], v[16:19], v[244:247], v[92:95]
	s_waitcnt lgkmcnt(0)
	v_mfma_f32_16x16x32_bf16 v[64:67], v[20:23], v[248:251], v[56:59]
	v_mfma_f32_16x16x32_bf16 v[56:59], v[28:31], v[244:247], v[100:103]
	v_mfma_f32_16x16x32_bf16 v[56:59], v[212:215], v[248:251], v[56:59]
	s_setprio 0
	s_setprio 1
	v_mfma_f32_16x16x32_bf16 v[68:71], v[216:219], v[24:27], v[108:111]
	v_mfma_f32_16x16x32_bf16 v[24:27], v[224:227], v[24:27], v[36:39]
	v_mfma_f32_16x16x32_bf16 v[116:119], v[228:231], v[32:35], v[24:27]
	v_mfma_f32_16x16x32_bf16 v[24:27], v[216:219], v[60:63], v[40:43]
	v_mfma_f32_16x16x32_bf16 v[108:111], v[220:223], v[232:235], v[24:27]
	v_mfma_f32_16x16x32_bf16 v[24:27], v[224:227], v[60:63], v[44:47]
	v_mfma_f32_16x16x32_bf16 v[100:103], v[228:231], v[232:235], v[24:27]
	v_mfma_f32_16x16x32_bf16 v[24:27], v[216:219], v[236:239], v[48:51]
	v_mfma_f32_16x16x32_bf16 v[92:95], v[220:223], v[240:243], v[24:27]
	v_mfma_f32_16x16x32_bf16 v[24:27], v[224:227], v[236:239], v[52:55]
	v_mfma_f32_16x16x32_bf16 v[84:87], v[228:231], v[240:243], v[24:27]
	v_mfma_f32_16x16x32_bf16 v[24:27], v[216:219], v[244:247], v[146:149]
	v_mfma_f32_16x16x32_bf16 v[60:63], v[220:223], v[248:251], v[24:27]
	v_mfma_f32_16x16x32_bf16 v[24:27], v[224:227], v[244:247], v[150:153]
	v_mfma_f32_16x16x32_bf16 v[124:127], v[220:223], v[32:35], v[68:71]
	v_mfma_f32_16x16x32_bf16 v[52:55], v[228:231], v[248:251], v[24:27]
	s_setprio 0
	s_barrier
	s_add_u32 s50, s12, 0x180
	ds_read_b128 v[36:39], v141 offset:49152
	ds_read_b128 v[44:47], v141 offset:50176
	ds_read_b128 v[146:149], v141 offset:51200
	ds_read_b128 v[150:153], v141 offset:52224
	ds_read_b128 v[232:235], v141 offset:53248
	ds_read_b128 v[236:239], v141 offset:54272
	ds_read_b128 v[240:243], v141 offset:55296
	ds_read_b128 v[244:247], v141 offset:56320
	s_addc_u32 s51, s13, 0
	s_add_i32 m0, s16, 0x18000
	s_nop 0
	global_load_lds_dwordx4 v1, s[50:51]
	s_nop 0
	s_add_i32 m0, s16, 0x1a000
	s_nop 0
	global_load_lds_dwordx4 v134, s[50:51]
	s_add_u32 s50, s12, 0x40180
	s_addc_u32 s51, s13, 0
	s_add_i32 m0, s16, 0x1c000
	s_nop 0
	global_load_lds_dwordx4 v1, s[50:51]
	s_nop 0
	s_add_i32 m0, s16, 0x1e000
	s_nop 0
	global_load_lds_dwordx4 v134, s[50:51]
	s_nop 0
	s_add_i32 m0, s16, 0x8000
	s_nop 0
	global_load_lds_dwordx4 v136, s[82:83]
	s_nop 0
	s_add_i32 m0, s16, 0xa000
	s_nop 0
	global_load_lds_dwordx4 v137, s[82:83]
	s_waitcnt vmcnt(8)
	s_waitcnt lgkmcnt(0)
	s_barrier
	s_setprio 1
	s_waitcnt lgkmcnt(7)
	v_mfma_f32_16x16x32_bf16 v[24:27], v[16:19], v[36:39], v[154:157]
	s_waitcnt lgkmcnt(6)
	v_mfma_f32_16x16x32_bf16 v[80:83], v[20:23], v[44:47], v[24:27]
	v_mfma_f32_16x16x32_bf16 v[24:27], v[28:31], v[36:39], v[158:161]
	v_mfma_f32_16x16x32_bf16 v[72:75], v[212:215], v[44:47], v[24:27]
	s_waitcnt lgkmcnt(5)
	v_mfma_f32_16x16x32_bf16 v[24:27], v[16:19], v[146:149], v[162:165]
	s_waitcnt lgkmcnt(4)
	v_mfma_f32_16x16x32_bf16 v[48:51], v[20:23], v[150:153], v[24:27]
	v_mfma_f32_16x16x32_bf16 v[24:27], v[28:31], v[146:149], v[166:169]
	v_mfma_f32_16x16x32_bf16 v[40:43], v[212:215], v[150:153], v[24:27]
	s_waitcnt lgkmcnt(3)
	v_mfma_f32_16x16x32_bf16 v[24:27], v[16:19], v[232:235], v[172:175]
	s_waitcnt lgkmcnt(1)
	v_mfma_f32_16x16x32_bf16 v[4:7], v[16:19], v[240:243], v[4:7]
	v_mfma_f32_16x16x32_bf16 v[32:35], v[20:23], v[236:239], v[24:27]
	v_mfma_f32_16x16x32_bf16 v[24:27], v[28:31], v[232:235], v[176:179]
	s_waitcnt lgkmcnt(0)
	v_mfma_f32_16x16x32_bf16 v[16:19], v[20:23], v[244:247], v[4:7]
	v_mfma_f32_16x16x32_bf16 v[4:7], v[28:31], v[240:243], v[8:11]
	v_mfma_f32_16x16x32_bf16 v[24:27], v[212:215], v[236:239], v[24:27]
	v_mfma_f32_16x16x32_bf16 v[8:11], v[212:215], v[244:247], v[4:7]
	s_setprio 0
	s_setprio 1
	v_mfma_f32_16x16x32_bf16 v[4:7], v[216:219], v[36:39], v[12:15]
	v_mfma_f32_16x16x32_bf16 v[76:79], v[220:223], v[44:47], v[4:7]
	v_mfma_f32_16x16x32_bf16 v[4:7], v[224:227], v[36:39], v[180:183]
	v_mfma_f32_16x16x32_bf16 v[68:71], v[228:231], v[44:47], v[4:7]
	v_mfma_f32_16x16x32_bf16 v[4:7], v[216:219], v[146:149], v[184:187]
	v_mfma_f32_16x16x32_bf16 v[44:47], v[220:223], v[150:153], v[4:7]
	v_mfma_f32_16x16x32_bf16 v[4:7], v[224:227], v[146:149], v[188:191]
	v_mfma_f32_16x16x32_bf16 v[36:39], v[228:231], v[150:153], v[4:7]
	v_mfma_f32_16x16x32_bf16 v[4:7], v[216:219], v[232:235], v[196:199]
	v_mfma_f32_16x16x32_bf16 v[28:31], v[220:223], v[236:239], v[4:7]
	v_mfma_f32_16x16x32_bf16 v[4:7], v[224:227], v[232:235], v[200:203]
	v_mfma_f32_16x16x32_bf16 v[20:23], v[228:231], v[236:239], v[4:7]
	v_mfma_f32_16x16x32_bf16 v[4:7], v[216:219], v[240:243], v[204:207]
	v_mfma_f32_16x16x32_bf16 v[12:15], v[220:223], v[244:247], v[4:7]
	v_mfma_f32_16x16x32_bf16 v[4:7], v[224:227], v[240:243], v[208:211]
	v_mfma_f32_16x16x32_bf16 v[4:7], v[228:231], v[244:247], v[4:7]
	s_setprio 0
	s_barrier
	s_lshl_b32 s50, s80, 6
	s_addk_i32 s50, 0x4000
	s_lshl_b64 s[52:53], s[80:81], 14
	s_add_u32 s82, s6, s52
	s_addc_u32 s83, s7, s53
	s_lshl_b32 s51, s80, 8
	s_and_b32 s51, s51, 0x400
	s_add_i32 s51, s51, 0
	s_add_i32 s51, s51, 0x24400

.LBB0_728:
	v_add_u32_e32 v137, 0x10000, v2
	v_add_u32_e32 v138, 0x14000, v2
	s_and_b64 s[2:3], exec, s[84:85]
	ds_read_b128 v[4:7], v137
	ds_read_b128 v[8:11], v137 offset:1024
	ds_read_b128 v[12:15], v137 offset:2048
	ds_read_b128 v[16:19], v137 offset:3072
	ds_read_b128 v[20:23], v138
	ds_read_b128 v[24:27], v138 offset:1024
	ds_read_b128 v[28:31], v138 offset:2048
	ds_read_b128 v[32:35], v138 offset:3072
	s_cselect_b32 s47, s6, s29
	s_add_u32 s12, s78, 0x100
	s_addc_u32 s13, s79, 0
	s_add_u32 s2, s78, 0x180
	s_addc_u32 s3, s79, 0
	s_add_u32 s6, s76, 0x100
	s_addc_u32 s7, s77, 0
	ds_read_b128 v[36:39], v136
	ds_read_b128 v[40:43], v136 offset:1024
	ds_read_b128 v[44:47], v136 offset:2048
	ds_read_b128 v[48:51], v136 offset:3072
	ds_read_b128 v[52:55], v136 offset:4096
	ds_read_b128 v[56:59], v136 offset:5120
	ds_read_b128 v[60:63], v136 offset:6144
	ds_read_b128 v[64:67], v136 offset:7168
	s_add_u32 s59, s78, s16
	s_addc_u32 s38, s79, 0
	s_add_u32 s26, s59, 0x80
	s_addc_u32 s27, s38, 0
	s_add_i32 m0, s43, 0xc000
	s_nop 0
	global_load_lds_dwordx4 v134, s[26:27]
	s_nop 0
	s_add_i32 m0, s43, 0xe000
	s_nop 0
	global_load_lds_dwordx4 v135, s[26:27]
	s_waitcnt vmcnt(8)
	s_waitcnt lgkmcnt(0)
	s_barrier
	s_setprio 1
	s_waitcnt lgkmcnt(3)
	v_mfma_f32_16x16x32_bf16 v[86:89], v[4:7], v[52:55], 0
	s_waitcnt lgkmcnt(2)
	v_mfma_f32_16x16x32_bf16 v[94:97], v[8:11], v[56:59], v[86:89]
	v_mfma_f32_16x16x32_bf16 v[86:89], v[12:15], v[52:55], 0
	v_mfma_f32_16x16x32_bf16 v[98:101], v[16:19], v[56:59], v[86:89]
	s_waitcnt lgkmcnt(1)
	v_mfma_f32_16x16x32_bf16 v[86:89], v[4:7], v[60:63], 0
	v_mfma_f32_16x16x32_bf16 v[68:71], v[4:7], v[36:39], 0
	v_mfma_f32_16x16x32_bf16 v[72:75], v[12:15], v[36:39], 0
	v_mfma_f32_16x16x32_bf16 v[78:81], v[4:7], v[44:47], 0
	v_mfma_f32_16x16x32_bf16 v[82:85], v[12:15], v[44:47], 0
	s_waitcnt lgkmcnt(0)
	v_mfma_f32_16x16x32_bf16 v[102:105], v[8:11], v[64:67], v[86:89]
	v_mfma_f32_16x16x32_bf16 v[86:89], v[12:15], v[60:63], 0
	v_mfma_f32_16x16x32_bf16 v[68:71], v[8:11], v[40:43], v[68:71]
	v_mfma_f32_16x16x32_bf16 v[74:77], v[16:19], v[40:43], v[72:75]
	v_mfma_f32_16x16x32_bf16 v[78:81], v[8:11], v[48:51], v[78:81]
	v_mfma_f32_16x16x32_bf16 v[82:85], v[16:19], v[48:51], v[82:85]
	v_mfma_f32_16x16x32_bf16 v[106:109], v[16:19], v[64:67], v[86:89]
	s_setprio 0
	s_setprio 1
	v_mfma_f32_16x16x32_bf16 v[86:89], v[20:23], v[36:39], 0
	v_mfma_f32_16x16x32_bf16 v[36:39], v[28:31], v[36:39], 0
	v_mfma_f32_16x16x32_bf16 v[110:113], v[24:27], v[40:43], v[86:89]
	v_mfma_f32_16x16x32_bf16 v[36:39], v[32:35], v[40:43], v[36:39]
	v_mfma_f32_16x16x32_bf16 v[40:43], v[20:23], v[44:47], 0
	v_mfma_f32_16x16x32_bf16 v[44:47], v[28:31], v[44:47], 0
	v_mfma_f32_16x16x32_bf16 v[40:43], v[24:27], v[48:51], v[40:43]
	v_mfma_f32_16x16x32_bf16 v[44:47], v[32:35], v[48:51], v[44:47]
	v_mfma_f32_16x16x32_bf16 v[48:51], v[20:23], v[52:55], 0
	v_mfma_f32_16x16x32_bf16 v[52:55], v[28:31], v[52:55], 0
	v_mfma_f32_16x16x32_bf16 v[48:51], v[24:27], v[56:59], v[48:51]
	v_mfma_f32_16x16x32_bf16 v[52:55], v[32:35], v[56:59], v[52:55]
	v_mfma_f32_16x16x32_bf16 v[56:59], v[20:23], v[60:63], 0
	v_mfma_f32_16x16x32_bf16 v[60:63], v[28:31], v[60:63], 0
	v_mfma_f32_16x16x32_bf16 v[56:59], v[24:27], v[64:67], v[56:59]
	v_mfma_f32_16x16x32_bf16 v[60:63], v[32:35], v[64:67], v[60:63]
	s_setprio 0
	s_barrier
	ds_read_b128 v[64:67], v136 offset:16384
	ds_read_b128 v[86:89], v136 offset:17408
	ds_read_b128 v[90:93], v136 offset:18432
	ds_read_b128 v[114:117], v136 offset:19456
	ds_read_b128 v[118:121], v136 offset:20480
	ds_read_b128 v[122:125], v136 offset:21504
	ds_read_b128 v[126:129], v136 offset:22528
	ds_read_b128 v[130:133], v136 offset:23552
	s_add_i32 m0, s43, 0x10000
	s_nop 0
	global_load_lds_dwordx4 v134, s[6:7]
	s_nop 0
	s_add_i32 m0, s43, 0x12000
	s_nop 0
	global_load_lds_dwordx4 v135, s[6:7]
	s_add_u32 s6, s6, s16
	s_addc_u32 s7, s7, 0
	s_add_i32 m0, s43, 0x14000
	s_nop 0
	global_load_lds_dwordx4 v134, s[6:7]
	s_nop 0
	s_add_i32 m0, s43, 0x16000
	s_nop 0
	global_load_lds_dwordx4 v135, s[6:7]
	s_nop 0
	s_add_i32 m0, s43, 0
	s_nop 0
	global_load_lds_dwordx4 v134, s[12:13]
	s_nop 0
	s_add_i32 m0, s43, 0x2000
	s_nop 0
	global_load_lds_dwordx4 v135, s[12:13]
	s_waitcnt vmcnt(8)
	s_waitcnt lgkmcnt(0)
	s_barrier
	s_setprio 1
	s_waitcnt lgkmcnt(7)
	v_mfma_f32_16x16x32_bf16 v[140:143], v[4:7], v[64:67], 0
	s_waitcnt lgkmcnt(5)
	v_mfma_f32_16x16x32_bf16 v[150:153], v[4:7], v[90:93], 0
	s_waitcnt lgkmcnt(3)
	v_mfma_f32_16x16x32_bf16 v[158:161], v[4:7], v[118:121], 0
	s_waitcnt lgkmcnt(1)
	v_mfma_f32_16x16x32_bf16 v[4:7], v[4:7], v[126:129], 0
	v_mfma_f32_16x16x32_bf16 v[146:149], v[12:15], v[64:67], 0
	v_mfma_f32_16x16x32_bf16 v[154:157], v[12:15], v[90:93], 0
	v_mfma_f32_16x16x32_bf16 v[162:165], v[12:15], v[118:121], 0
	s_waitcnt lgkmcnt(0)
	v_mfma_f32_16x16x32_bf16 v[166:169], v[8:11], v[130:133], v[4:7]
	v_mfma_f32_16x16x32_bf16 v[4:7], v[12:15], v[126:129], 0
	v_mfma_f32_16x16x32_bf16 v[142:145], v[8:11], v[86:89], v[140:143]
	v_mfma_f32_16x16x32_bf16 v[146:149], v[16:19], v[86:89], v[146:149]
	v_mfma_f32_16x16x32_bf16 v[150:153], v[8:11], v[114:117], v[150:153]
	v_mfma_f32_16x16x32_bf16 v[154:157], v[16:19], v[114:117], v[154:157]
	v_mfma_f32_16x16x32_bf16 v[158:161], v[8:11], v[122:125], v[158:161]
	v_mfma_f32_16x16x32_bf16 v[162:165], v[16:19], v[122:125], v[162:165]
	v_mfma_f32_16x16x32_bf16 v[172:175], v[16:19], v[130:133], v[4:7]
	s_setprio 0
	s_setprio 1
	v_mfma_f32_16x16x32_bf16 v[4:7], v[20:23], v[64:67], 0
	v_mfma_f32_16x16x32_bf16 v[176:179], v[24:27], v[86:89], v[4:7]
	v_mfma_f32_16x16x32_bf16 v[4:7], v[28:31], v[64:67], 0
	v_mfma_f32_16x16x32_bf16 v[64:67], v[32:35], v[86:89], v[4:7]
	v_mfma_f32_16x16x32_bf16 v[4:7], v[20:23], v[90:93], 0
	v_mfma_f32_16x16x32_bf16 v[180:183], v[24:27], v[114:117], v[4:7]
	v_mfma_f32_16x16x32_bf16 v[4:7], v[28:31], v[90:93], 0
	v_mfma_f32_16x16x32_bf16 v[184:187], v[32:35], v[114:117], v[4:7]
	v_mfma_f32_16x16x32_bf16 v[4:7], v[20:23], v[118:121], 0
	v_mfma_f32_16x16x32_bf16 v[196:199], v[24:27], v[122:125], v[4:7]
	v_mfma_f32_16x16x32_bf16 v[4:7], v[28:31], v[118:121], 0
	v_mfma_f32_16x16x32_bf16 v[200:203], v[32:35], v[122:125], v[4:7]
	v_mfma_f32_16x16x32_bf16 v[4:7], v[20:23], v[126:129], 0
	v_mfma_f32_16x16x32_bf16 v[204:207], v[24:27], v[130:133], v[4:7]
	v_mfma_f32_16x16x32_bf16 v[4:7], v[28:31], v[126:129], 0
	v_mfma_f32_16x16x32_bf16 v[208:211], v[32:35], v[130:133], v[4:7]
	s_setprio 0
	s_barrier
	v_add_u32_e32 v139, 0x18000, v2
	v_add_u32_e32 v140, 0x1c000, v2
	ds_read_b128 v[18:21], v139
	ds_read_b128 v[212:215], v139 offset:1024
	ds_read_b128 v[216:219], v139 offset:2048
	ds_read_b128 v[220:223], v139 offset:3072
	ds_read_b128 v[224:227], v140
	ds_read_b128 v[228:231], v140 offset:1024
	ds_read_b128 v[232:235], v140 offset:2048
	ds_read_b128 v[236:239], v140 offset:3072
	ds_read_b128 v[4:7], v136 offset:32768
	ds_read_b128 v[8:11], v136 offset:33792
	ds_read_b128 v[12:15], v136 offset:34816
	ds_read_b128 v[22:25], v136 offset:35840
	ds_read_b128 v[26:29], v136 offset:36864
	ds_read_b128 v[30:33], v136 offset:37888
	ds_read_b128 v[130:133], v136 offset:38912
	ds_read_b128 v[240:243], v136 offset:39936
	s_add_u32 s6, s12, s16
	s_addc_u32 s7, s13, 0
	s_add_i32 m0, s43, 0x4000
	s_nop 0
	global_load_lds_dwordx4 v134, s[6:7]
	s_nop 0
	s_add_i32 m0, s43, 0x6000
	s_nop 0
	global_load_lds_dwordx4 v135, s[6:7]
	s_waitcnt vmcnt(8)
	s_waitcnt lgkmcnt(0)
	s_barrier
	s_setprio 1
	s_waitcnt lgkmcnt(7)
	v_mfma_f32_16x16x32_bf16 v[74:77], v[216:219], v[4:7], v[74:77]
	s_waitcnt lgkmcnt(6)
	v_mfma_f32_16x16x32_bf16 v[86:89], v[220:223], v[8:11], v[74:77]
	s_waitcnt lgkmcnt(5)
	v_mfma_f32_16x16x32_bf16 v[74:77], v[18:21], v[12:15], v[78:81]
	v_mfma_f32_16x16x32_bf16 v[78:81], v[216:219], v[12:15], v[82:85]
	s_waitcnt lgkmcnt(3)
	v_mfma_f32_16x16x32_bf16 v[82:85], v[216:219], v[26:29], v[98:101]
	v_mfma_f32_16x16x32_bf16 v[68:71], v[18:21], v[4:7], v[68:71]
	v_mfma_f32_16x16x32_bf16 v[90:93], v[220:223], v[22:25], v[78:81]
	v_mfma_f32_16x16x32_bf16 v[78:81], v[18:21], v[26:29], v[94:97]
	s_waitcnt lgkmcnt(2)
	v_mfma_f32_16x16x32_bf16 v[94:97], v[220:223], v[30:33], v[82:85]
	s_waitcnt lgkmcnt(1)
	v_mfma_f32_16x16x32_bf16 v[82:85], v[18:21], v[130:133], v[102:105]
	v_mfma_f32_16x16x32_bf16 v[98:101], v[216:219], v[130:133], v[106:109]
	v_mfma_f32_16x16x32_bf16 v[70:73], v[212:215], v[8:11], v[68:71]
	v_mfma_f32_16x16x32_bf16 v[74:77], v[212:215], v[22:25], v[74:77]
	v_mfma_f32_16x16x32_bf16 v[78:81], v[212:215], v[30:33], v[78:81]
	s_waitcnt lgkmcnt(0)
	v_mfma_f32_16x16x32_bf16 v[82:85], v[212:215], v[240:243], v[82:85]
	v_mfma_f32_16x16x32_bf16 v[98:101], v[220:223], v[240:243], v[98:101]
	s_setprio 0
	s_setprio 1
	v_mfma_f32_16x16x32_bf16 v[102:105], v[224:227], v[4:7], v[110:113]
	v_mfma_f32_16x16x32_bf16 v[4:7], v[232:235], v[4:7], v[36:39]
	v_mfma_f32_16x16x32_bf16 v[118:121], v[236:239], v[8:11], v[4:7]
	v_mfma_f32_16x16x32_bf16 v[4:7], v[224:227], v[12:15], v[40:43]
	v_mfma_f32_16x16x32_bf16 v[106:109], v[228:231], v[22:25], v[4:7]
	v_mfma_f32_16x16x32_bf16 v[4:7], v[232:235], v[12:15], v[44:47]
	v_mfma_f32_16x16x32_bf16 v[122:125], v[236:239], v[22:25], v[4:7]
	v_mfma_f32_16x16x32_bf16 v[4:7], v[224:227], v[26:29], v[48:51]
	v_mfma_f32_16x16x32_bf16 v[110:113], v[228:231], v[30:33], v[4:7]
	v_mfma_f32_16x16x32_bf16 v[4:7], v[232:235], v[26:29], v[52:55]
	v_mfma_f32_16x16x32_bf16 v[126:129], v[236:239], v[30:33], v[4:7]
	v_mfma_f32_16x16x32_bf16 v[4:7], v[224:227], v[130:133], v[56:59]
	v_mfma_f32_16x16x32_bf16 v[114:117], v[228:231], v[240:243], v[4:7]
	v_mfma_f32_16x16x32_bf16 v[4:7], v[232:235], v[130:133], v[60:63]
	v_mfma_f32_16x16x32_bf16 v[102:105], v[228:231], v[8:11], v[102:105]
	v_mfma_f32_16x16x32_bf16 v[130:133], v[236:239], v[240:243], v[4:7]
	s_setprio 0
	s_barrier
	s_add_u32 s6, s76, 0x180
	ds_read_b128 v[42:45], v136 offset:49152
	ds_read_b128 v[46:49], v136 offset:50176
	ds_read_b128 v[50:53], v136 offset:51200
	ds_read_b128 v[58:61], v136 offset:52224
	ds_read_b128 v[240:243], v136 offset:53248
	ds_read_b128 v[244:247], v136 offset:54272
	ds_read_b128 v[248:251], v136 offset:55296
	ds_read_b128 v[188:191], v136 offset:56320
	s_addc_u32 s7, s77, 0
	s_add_i32 m0, s43, 0x18000
	s_nop 0
	global_load_lds_dwordx4 v134, s[6:7]
	s_nop 0
	s_add_i32 m0, s43, 0x1a000
	s_nop 0
	global_load_lds_dwordx4 v135, s[6:7]
	s_add_u32 s6, s6, s16
	s_addc_u32 s7, s7, 0
	s_add_i32 m0, s43, 0x1c000
	s_nop 0
	global_load_lds_dwordx4 v134, s[6:7]
	s_nop 0
	s_add_i32 m0, s43, 0x1e000
	s_nop 0
	global_load_lds_dwordx4 v135, s[6:7]
	s_nop 0
	s_add_i32 m0, s43, 0x8000
	s_nop 0
	global_load_lds_dwordx4 v134, s[2:3]
	s_nop 0
	s_add_i32 m0, s43, 0xa000
	s_nop 0
	global_load_lds_dwordx4 v135, s[2:3]
	s_waitcnt vmcnt(8)
	s_waitcnt lgkmcnt(0)
	s_barrier
	s_setprio 1
	s_waitcnt lgkmcnt(7)
	v_mfma_f32_16x16x32_bf16 v[10:13], v[216:219], v[42:45], v[146:149]
	s_waitcnt lgkmcnt(5)
	v_mfma_f32_16x16x32_bf16 v[14:17], v[216:219], v[50:53], v[154:157]
	v_mfma_f32_16x16x32_bf16 v[4:7], v[18:21], v[42:45], v[142:145]
	v_mfma_f32_16x16x32_bf16 v[22:25], v[220:223], v[46:49], v[10:13]
	v_mfma_f32_16x16x32_bf16 v[10:13], v[18:21], v[50:53], v[150:153]
	s_waitcnt lgkmcnt(4)
	v_mfma_f32_16x16x32_bf16 v[26:29], v[220:223], v[58:61], v[14:17]
	s_waitcnt lgkmcnt(3)
	v_mfma_f32_16x16x32_bf16 v[14:17], v[18:21], v[240:243], v[158:161]
	v_mfma_f32_16x16x32_bf16 v[30:33], v[216:219], v[240:243], v[162:165]
	s_waitcnt lgkmcnt(1)
	v_mfma_f32_16x16x32_bf16 v[18:21], v[18:21], v[248:251], v[166:169]
	v_mfma_f32_16x16x32_bf16 v[34:37], v[216:219], v[248:251], v[172:175]
	v_mfma_f32_16x16x32_bf16 v[6:9], v[212:215], v[46:49], v[4:7]
	v_mfma_f32_16x16x32_bf16 v[10:13], v[212:215], v[58:61], v[10:13]
	v_mfma_f32_16x16x32_bf16 v[14:17], v[212:215], v[244:247], v[14:17]
	v_mfma_f32_16x16x32_bf16 v[30:33], v[220:223], v[244:247], v[30:33]
	s_waitcnt lgkmcnt(0)
	v_mfma_f32_16x16x32_bf16 v[18:21], v[212:215], v[188:191], v[18:21]
	v_mfma_f32_16x16x32_bf16 v[34:37], v[220:223], v[188:191], v[34:37]
	s_setprio 0
	s_setprio 1
	v_mfma_f32_16x16x32_bf16 v[38:41], v[224:227], v[42:45], v[176:179]
	v_mfma_f32_16x16x32_bf16 v[42:45], v[232:235], v[42:45], v[64:67]
	v_mfma_f32_16x16x32_bf16 v[38:41], v[228:231], v[46:49], v[38:41]
	v_mfma_f32_16x16x32_bf16 v[54:57], v[236:239], v[46:49], v[42:45]
	v_mfma_f32_16x16x32_bf16 v[42:45], v[224:227], v[50:53], v[180:183]
	v_mfma_f32_16x16x32_bf16 v[46:49], v[232:235], v[50:53], v[184:187]
	v_mfma_f32_16x16x32_bf16 v[50:53], v[232:235], v[240:243], v[200:203]
	v_mfma_f32_16x16x32_bf16 v[42:45], v[228:231], v[58:61], v[42:45]
	v_mfma_f32_16x16x32_bf16 v[58:61], v[236:239], v[58:61], v[46:49]
	v_mfma_f32_16x16x32_bf16 v[46:49], v[224:227], v[240:243], v[196:199]
	v_mfma_f32_16x16x32_bf16 v[62:65], v[236:239], v[244:247], v[50:53]
	v_mfma_f32_16x16x32_bf16 v[50:53], v[224:227], v[248:251], v[204:207]
	v_mfma_f32_16x16x32_bf16 v[66:69], v[232:235], v[248:251], v[208:211]
	v_mfma_f32_16x16x32_bf16 v[46:49], v[228:231], v[244:247], v[46:49]
	v_mfma_f32_16x16x32_bf16 v[50:53], v[228:231], v[188:191], v[50:53]
	v_mfma_f32_16x16x32_bf16 v[66:69], v[236:239], v[188:191], v[66:69]
	s_setprio 0
	s_barrier
	s_add_i32 s2, s47, 1
	s_lshl_b32 s72, s47, 6
	s_and_b32 s3, s2, 31
	s_lshl_b32 s2, s2, 6
	s_add_i32 s6, s72, 0x9000
	s_add_i32 s7, s72, 0x8000
	s_add_i32 s18, s72, 0x7000
	s_addk_i32 s2, 0x6000
	s_cmp_eq_u32 s3, 0
	s_cselect_b32 s26, 0, 32
	s_cselect_b32 s27, 0, s2
	s_add_i32 s40, s72, 0x6000
	s_add_i32 s41, s72, 0x5000
	s_and_b32 s2, s47, 31
	s_add_i32 s3, s72, 0x4fc0
	s_cmp_eq_u32 s2, 0
	s_cselect_b32 s50, 0, 0x48
	s_cselect_b32 s52, 0, s3
	s_add_i32 s58, s72, 0x4000
	s_addk_i32 s72, 0x3000
	s_mov_b32 s90, 2
	s_branch .LBB0_731

.LBB0_1042:
	v_mov_b32_e32 v2, v0
	s_lshl_b32 s2, s19, 14
	v_ashrrev_i32_e32 v4, 1, v2
	v_ashrrev_i32_e32 v5, 31, v4
	s_add_u32 s2, s20, s2
	v_and_b32_e32 v11, 1, v2
	s_addc_u32 s3, s36, 0
	s_waitcnt vmcnt(18)
	v_lshlrev_b64 v[12:13], 6, v[4:5]
	v_lshl_add_u64 v[12:13], s[2:3], 0, v[12:13]
	v_lshlrev_b32_e32 v2, 5, v11
	s_waitcnt vmcnt(10)
	v_lshl_add_u64 v[20:21], v[12:13], 0, v[2:3]
	global_load_dwordx4 v[12:15], v[20:21], off sc1
	global_load_dwordx4 v[16:19], v[20:21], off offset:16 sc1
	s_waitcnt lgkmcnt(0)
	s_add_u32 s51, s70, 0x2a00000
	s_addc_u32 s97, s71, 0
	s_lshl_b32 s2, s19, 19
	s_add_u32 s62, s51, s2
	s_addc_u32 s63, s97, 0
	v_lshl_add_u32 v147, v7, 11, v8
	s_add_i32 m0, s69, 0
	s_nop 0
	global_load_lds_dwordx4 v147, s[62:63]
	s_ashr_i32 s2, s14, 8
	v_lshl_add_u32 v148, v9, 11, v10
	s_add_i32 m0, s69, 0x2000
	s_nop 0
	global_load_lds_dwordx4 v148, s[62:63]
	s_add_u32 s12, s62, 0x40000
	s_addc_u32 s13, s63, 0
	s_add_i32 m0, s69, 0x4000
	s_nop 0
	global_load_lds_dwordx4 v147, s[12:13]
	s_nop 0
	s_add_i32 m0, s69, 0x6000
	s_nop 0
	global_load_lds_dwordx4 v148, s[12:13]
	s_waitcnt vmcnt(4)
	s_nop 0
	v_add_f32_e32 v2, v12, v13
	v_add_f32_e32 v5, v14, v15
	v_add_f32_e32 v2, v2, v5
	v_add_f32_e32 v5, v16, v17
	v_add_f32_e32 v12, v18, v19
	v_add_f32_e32 v5, v5, v12
	v_and_b32_e32 v12, 64, v192
	v_add_f32_e32 v2, v2, v5
	v_xor_b32_e32 v5, 1, v192
	v_add_u32_e32 v12, 64, v12
	v_cmp_lt_i32_e32 vcc, v5, v12
	s_nop 1
	v_cndmask_b32_e32 v5, v192, v5, vcc
	v_lshlrev_b32_e32 v5, 2, v5
	ds_bpermute_b32 v5, v5, v2
	v_cmp_eq_u32_e32 vcc, 0, v11
	s_and_saveexec_b64 s[2:3], vcc
	s_cbranch_execz .LBB0_1044
	s_waitcnt lgkmcnt(0)
	v_add_f32_e32 v2, v2, v5
	v_fmamk_f32 v2, v2, 0x3a800000, v254
	s_lshl_b32 s7, s19, 8
	v_rsq_f32_e32 v5, v2
	s_and_b32 s7, s7, 0x400
	s_add_i32 s7, s7, 0
	v_lshl_add_u32 v4, v4, 2, s7
	v_add_u32_e32 v4, 0x24400, v4
	ds_write2st64_b32 v4, v5, v2 offset1:8
.LBB0_1044:
	s_or_b64 exec, exec, s[2:3]
	s_ashr_i32 s2, s14, 8
	s_branch .Lafter_A3

.Lafter_A3:
	s_cmp_eq_u32 s2, 1
	s_cselect_b64 s[70:71], -1, 0
	s_cmp_lg_u32 s2, 1
	s_cbranch_scc1 .LBB0_1047
	s_barrier

.LBB0_1071:
	s_add_i32 s16, s38, 1
	s_add_i32 s3, s16, s35
	s_mul_i32 s3, s3, s23
	s_add_i32 s3, s3, s22
	s_add_i32 s12, s18, s3
	s_cmp_lt_i32 s12, s2
	s_cselect_b64 s[78:79], -1, 0
	s_cmp_ge_i32 s12, s2
	s_cselect_b64 s[74:75], -1, 0
	s_lshr_b32 s2, s2, 1
	s_cmp_lt_i32 s12, s2
	s_cselect_b32 s2, 0, s2
	s_cselect_b32 s13, 0, 4
	s_sub_i32 s2, s12, s2
	s_and_b32 s3, s3, 3
	s_ashr_i32 s37, s2, 2
	s_or_b32 s2, s3, s13
	s_or_b32 s53, s2, s28
	s_and_b64 s[2:3], s[78:79], exec
	s_cselect_b32 s82, s53, s7
	s_cselect_b32 s2, s37, s6
	s_ashr_i32 s83, s82, 31
	s_lshl_b64 s[6:7], s[82:83], 19
	s_add_u32 s76, s51, s6
	s_addc_u32 s77, s97, s7
	s_ashr_i32 s3, s2, 31
	s_lshl_b64 s[2:3], s[2:3], 19
	s_add_u32 s80, s56, s2
	s_addc_u32 s81, s96, s3
	s_add_u32 s12, s62, 0x100
	s_addc_u32 s13, s63, 0
	v_add_u32_e32 v134, 0x10000, v151
	v_add_u32_e32 v135, 0x14000, v151
	s_add_u32 s2, s62, 0x180
	ds_read_b128 v[4:7], v134
	ds_read_b128 v[8:11], v134 offset:1024
	ds_read_b128 v[12:15], v134 offset:2048
	ds_read_b128 v[16:19], v134 offset:3072
	ds_read_b128 v[20:23], v135
	ds_read_b128 v[24:27], v135 offset:1024
	ds_read_b128 v[28:31], v135 offset:2048
	ds_read_b128 v[32:35], v135 offset:3072
	s_addc_u32 s3, s63, 0
	s_and_b64 s[6:7], s[78:79], exec
	s_cselect_b32 s33, s77, s63
	s_cselect_b32 s39, s76, s62
	s_add_u32 s6, s64, 0x100
	s_addc_u32 s7, s65, 0
	s_and_b64 s[26:27], s[78:79], exec
	s_mov_b32 s29, 2
	s_cselect_b32 s54, s81, s65
	s_cselect_b32 s47, s80, s64
	ds_read_b128 v[36:39], v152
	ds_read_b128 v[40:43], v152 offset:1024
	ds_read_b128 v[44:47], v152 offset:2048
	ds_read_b128 v[48:51], v152 offset:3072
	ds_read_b128 v[52:55], v152 offset:4096
	ds_read_b128 v[56:59], v152 offset:5120
	ds_read_b128 v[60:63], v152 offset:6144
	ds_read_b128 v[64:67], v152 offset:7168
	s_add_u32 s26, s62, 0x40080
	s_addc_u32 s27, s63, 0
	s_add_i32 m0, s69, 0xc000
	s_nop 0
	global_load_lds_dwordx4 v147, s[26:27]
	s_nop 0
	s_add_i32 m0, s69, 0xe000
	s_nop 0
	global_load_lds_dwordx4 v148, s[26:27]
	s_waitcnt vmcnt(8)
	s_waitcnt lgkmcnt(0)
	s_barrier
	s_setprio 1
	s_waitcnt lgkmcnt(1)
	v_mfma_f32_16x16x32_bf16 v[92:95], v[4:7], v[60:63], 0
	v_mfma_f32_16x16x32_bf16 v[68:71], v[4:7], v[36:39], 0
	v_mfma_f32_16x16x32_bf16 v[72:75], v[12:15], v[36:39], 0
	v_mfma_f32_16x16x32_bf16 v[76:79], v[4:7], v[44:47], 0
	v_mfma_f32_16x16x32_bf16 v[80:83], v[12:15], v[44:47], 0
	v_mfma_f32_16x16x32_bf16 v[84:87], v[4:7], v[52:55], 0
	v_mfma_f32_16x16x32_bf16 v[88:91], v[12:15], v[52:55], 0
	s_waitcnt lgkmcnt(0)
	v_mfma_f32_16x16x32_bf16 v[96:99], v[8:11], v[64:67], v[92:95]
	v_mfma_f32_16x16x32_bf16 v[92:95], v[12:15], v[60:63], 0
	v_mfma_f32_16x16x32_bf16 v[68:71], v[8:11], v[40:43], v[68:71]
	v_mfma_f32_16x16x32_bf16 v[72:75], v[16:19], v[40:43], v[72:75]
	v_mfma_f32_16x16x32_bf16 v[76:79], v[8:11], v[48:51], v[76:79]
	v_mfma_f32_16x16x32_bf16 v[80:83], v[16:19], v[48:51], v[80:83]
	v_mfma_f32_16x16x32_bf16 v[84:87], v[8:11], v[56:59], v[84:87]
	v_mfma_f32_16x16x32_bf16 v[88:91], v[16:19], v[56:59], v[88:91]
	v_mfma_f32_16x16x32_bf16 v[104:107], v[16:19], v[64:67], v[92:95]
	s_setprio 0
	s_setprio 1
	v_mfma_f32_16x16x32_bf16 v[92:95], v[20:23], v[36:39], 0
	v_mfma_f32_16x16x32_bf16 v[36:39], v[28:31], v[36:39], 0
	v_mfma_f32_16x16x32_bf16 v[112:115], v[24:27], v[40:43], v[92:95]
	v_mfma_f32_16x16x32_bf16 v[36:39], v[32:35], v[40:43], v[36:39]
	v_mfma_f32_16x16x32_bf16 v[40:43], v[20:23], v[44:47], 0
	v_mfma_f32_16x16x32_bf16 v[44:47], v[28:31], v[44:47], 0
	v_mfma_f32_16x16x32_bf16 v[40:43], v[24:27], v[48:51], v[40:43]
	v_mfma_f32_16x16x32_bf16 v[44:47], v[32:35], v[48:51], v[44:47]
	v_mfma_f32_16x16x32_bf16 v[48:51], v[20:23], v[52:55], 0
	v_mfma_f32_16x16x32_bf16 v[52:55], v[28:31], v[52:55], 0
	v_mfma_f32_16x16x32_bf16 v[48:51], v[24:27], v[56:59], v[48:51]
	v_mfma_f32_16x16x32_bf16 v[52:55], v[32:35], v[56:59], v[52:55]
	v_mfma_f32_16x16x32_bf16 v[56:59], v[20:23], v[60:63], 0
	v_mfma_f32_16x16x32_bf16 v[60:63], v[28:31], v[60:63], 0
	v_mfma_f32_16x16x32_bf16 v[56:59], v[24:27], v[64:67], v[56:59]
	v_mfma_f32_16x16x32_bf16 v[60:63], v[32:35], v[64:67], v[60:63]
	s_setprio 0
	s_barrier
	ds_read_b128 v[64:67], v152 offset:16384
	ds_read_b128 v[92:95], v152 offset:17408
	ds_read_b128 v[100:103], v152 offset:18432
	ds_read_b128 v[108:111], v152 offset:19456
	ds_read_b128 v[116:119], v152 offset:20480
	ds_read_b128 v[120:123], v152 offset:21504
	ds_read_b128 v[124:127], v152 offset:22528
	ds_read_b128 v[128:131], v152 offset:23552
	s_add_i32 m0, s69, 0x10000
	s_nop 0
	global_load_lds_dwordx4 v1, s[6:7]
	s_nop 0
	s_add_i32 m0, s69, 0x12000
	s_nop 0
	global_load_lds_dwordx4 v146, s[6:7]
	s_add_u32 s6, s64, 0x40100
	s_addc_u32 s7, s65, 0
	s_add_i32 m0, s69, 0x14000
	s_nop 0
	global_load_lds_dwordx4 v1, s[6:7]
	s_nop 0
	s_add_i32 m0, s69, 0x16000
	s_nop 0
	global_load_lds_dwordx4 v146, s[6:7]
	s_nop 0
	s_add_i32 m0, s69, 0
	s_nop 0
	global_load_lds_dwordx4 v147, s[12:13]
	s_nop 0
	s_add_i32 m0, s69, 0x2000
	s_nop 0
	global_load_lds_dwordx4 v148, s[12:13]
	s_waitcnt vmcnt(8)
	s_waitcnt lgkmcnt(0)
	s_barrier
	s_setprio 1
	s_waitcnt lgkmcnt(7)
	v_mfma_f32_16x16x32_bf16 v[136:139], v[4:7], v[64:67], 0
	s_waitcnt lgkmcnt(5)
	v_mfma_f32_16x16x32_bf16 v[154:157], v[4:7], v[100:103], 0
	s_waitcnt lgkmcnt(3)
	v_mfma_f32_16x16x32_bf16 v[162:165], v[4:7], v[116:119], 0
	s_waitcnt lgkmcnt(1)
	v_mfma_f32_16x16x32_bf16 v[4:7], v[4:7], v[124:127], 0
	v_mfma_f32_16x16x32_bf16 v[138:141], v[8:11], v[92:95], v[136:139]
	v_mfma_f32_16x16x32_bf16 v[154:157], v[8:11], v[108:111], v[154:157]
	v_mfma_f32_16x16x32_bf16 v[162:165], v[8:11], v[120:123], v[162:165]
	s_waitcnt lgkmcnt(0)
	v_mfma_f32_16x16x32_bf16 v[4:7], v[8:11], v[128:131], v[4:7]
	v_mfma_f32_16x16x32_bf16 v[8:11], v[12:15], v[124:127], 0
	v_mfma_f32_16x16x32_bf16 v[142:145], v[12:15], v[64:67], 0
	v_mfma_f32_16x16x32_bf16 v[158:161], v[12:15], v[100:103], 0
	v_mfma_f32_16x16x32_bf16 v[166:169], v[12:15], v[116:119], 0
	v_mfma_f32_16x16x32_bf16 v[8:11], v[16:19], v[128:131], v[8:11]
	v_mfma_f32_16x16x32_bf16 v[142:145], v[16:19], v[92:95], v[142:145]
	v_mfma_f32_16x16x32_bf16 v[158:161], v[16:19], v[108:111], v[158:161]
	v_mfma_f32_16x16x32_bf16 v[166:169], v[16:19], v[120:123], v[166:169]
	s_setprio 0
	s_setprio 1
	v_mfma_f32_16x16x32_bf16 v[12:15], v[20:23], v[64:67], 0
	v_mfma_f32_16x16x32_bf16 v[16:19], v[24:27], v[92:95], v[12:15]
	v_mfma_f32_16x16x32_bf16 v[12:15], v[28:31], v[64:67], 0
	v_mfma_f32_16x16x32_bf16 v[172:175], v[32:35], v[92:95], v[12:15]
	v_mfma_f32_16x16x32_bf16 v[12:15], v[20:23], v[100:103], 0
	v_mfma_f32_16x16x32_bf16 v[176:179], v[24:27], v[108:111], v[12:15]
	v_mfma_f32_16x16x32_bf16 v[12:15], v[28:31], v[100:103], 0
	v_mfma_f32_16x16x32_bf16 v[180:183], v[32:35], v[108:111], v[12:15]
	v_mfma_f32_16x16x32_bf16 v[12:15], v[20:23], v[116:119], 0
	v_mfma_f32_16x16x32_bf16 v[184:187], v[24:27], v[120:123], v[12:15]
	v_mfma_f32_16x16x32_bf16 v[12:15], v[28:31], v[116:119], 0
	v_mfma_f32_16x16x32_bf16 v[204:207], v[32:35], v[120:123], v[12:15]
	v_mfma_f32_16x16x32_bf16 v[12:15], v[20:23], v[124:127], 0
	v_mfma_f32_16x16x32_bf16 v[208:211], v[24:27], v[128:131], v[12:15]
	v_mfma_f32_16x16x32_bf16 v[12:15], v[28:31], v[124:127], 0
	v_mfma_f32_16x16x32_bf16 v[212:215], v[32:35], v[128:131], v[12:15]
	s_setprio 0
	s_barrier
	v_add_u32_e32 v136, 0x18000, v151
	v_add_u32_e32 v137, 0x1c000, v151
	s_nop 2
	ds_read_b128 v[12:15], v136
	ds_read_b128 v[24:27], v136 offset:1024
	ds_read_b128 v[32:35], v136 offset:2048
	ds_read_b128 v[216:219], v136 offset:3072
	ds_read_b128 v[220:223], v137
	ds_read_b128 v[224:227], v137 offset:1024
	ds_read_b128 v[228:231], v137 offset:2048
	ds_read_b128 v[232:235], v137 offset:3072
	ds_read_b128 v[20:23], v152 offset:32768
	ds_read_b128 v[28:31], v152 offset:33792
	ds_read_b128 v[236:239], v152 offset:34816
	ds_read_b128 v[240:243], v152 offset:35840
	ds_read_b128 v[244:247], v152 offset:36864
	ds_read_b128 v[248:251], v152 offset:37888
	ds_read_b128 v[200:203], v152 offset:38912
	ds_read_b128 v[196:199], v152 offset:39936
	s_add_u32 s6, s62, 0x40100
	s_addc_u32 s7, s63, 0
	s_add_i32 m0, s69, 0x4000
	s_nop 0
	global_load_lds_dwordx4 v147, s[6:7]
	s_nop 0
	s_add_i32 m0, s69, 0x6000
	s_nop 0
	global_load_lds_dwordx4 v148, s[6:7]
	s_waitcnt vmcnt(8)
	s_waitcnt lgkmcnt(0)
	s_barrier
	s_setprio 1
	s_waitcnt lgkmcnt(7)
	v_mfma_f32_16x16x32_bf16 v[64:67], v[12:15], v[20:23], v[68:71]
	s_waitcnt lgkmcnt(6)
	v_mfma_f32_16x16x32_bf16 v[124:127], v[24:27], v[28:31], v[64:67]
	v_mfma_f32_16x16x32_bf16 v[64:67], v[32:35], v[20:23], v[72:75]
	v_mfma_f32_16x16x32_bf16 v[116:119], v[216:219], v[28:31], v[64:67]
	s_waitcnt lgkmcnt(5)
	v_mfma_f32_16x16x32_bf16 v[64:67], v[12:15], v[236:239], v[76:79]
	s_waitcnt lgkmcnt(4)
	v_mfma_f32_16x16x32_bf16 v[108:111], v[24:27], v[240:243], v[64:67]
	v_mfma_f32_16x16x32_bf16 v[64:67], v[32:35], v[236:239], v[80:83]
	v_mfma_f32_16x16x32_bf16 v[100:103], v[216:219], v[240:243], v[64:67]
	s_waitcnt lgkmcnt(3)
	v_mfma_f32_16x16x32_bf16 v[64:67], v[12:15], v[244:247], v[84:87]
	s_waitcnt lgkmcnt(2)
	v_mfma_f32_16x16x32_bf16 v[92:95], v[24:27], v[248:251], v[64:67]
	v_mfma_f32_16x16x32_bf16 v[64:67], v[32:35], v[244:247], v[88:91]
	v_mfma_f32_16x16x32_bf16 v[84:87], v[216:219], v[248:251], v[64:67]
	s_waitcnt lgkmcnt(1)
	v_mfma_f32_16x16x32_bf16 v[64:67], v[12:15], v[200:203], v[96:99]
	s_waitcnt lgkmcnt(0)
	v_mfma_f32_16x16x32_bf16 v[76:79], v[24:27], v[196:199], v[64:67]
	v_mfma_f32_16x16x32_bf16 v[64:67], v[32:35], v[200:203], v[104:107]
	v_mfma_f32_16x16x32_bf16 v[64:67], v[216:219], v[196:199], v[64:67]
	s_setprio 0
	s_setprio 1
	v_mfma_f32_16x16x32_bf16 v[68:71], v[220:223], v[20:23], v[112:115]
	v_mfma_f32_16x16x32_bf16 v[20:23], v[228:231], v[20:23], v[36:39]
	v_mfma_f32_16x16x32_bf16 v[120:123], v[232:235], v[28:31], v[20:23]
	v_mfma_f32_16x16x32_bf16 v[20:23], v[220:223], v[236:239], v[40:43]
	v_mfma_f32_16x16x32_bf16 v[112:115], v[224:227], v[240:243], v[20:23]
	v_mfma_f32_16x16x32_bf16 v[20:23], v[228:231], v[236:239], v[44:47]
	v_mfma_f32_16x16x32_bf16 v[104:107], v[232:235], v[240:243], v[20:23]
	v_mfma_f32_16x16x32_bf16 v[20:23], v[220:223], v[244:247], v[48:51]
	v_mfma_f32_16x16x32_bf16 v[96:99], v[224:227], v[248:251], v[20:23]
	v_mfma_f32_16x16x32_bf16 v[20:23], v[228:231], v[244:247], v[52:55]
	v_mfma_f32_16x16x32_bf16 v[88:91], v[232:235], v[248:251], v[20:23]
	v_mfma_f32_16x16x32_bf16 v[20:23], v[220:223], v[200:203], v[56:59]
	v_mfma_f32_16x16x32_bf16 v[80:83], v[224:227], v[196:199], v[20:23]
	v_mfma_f32_16x16x32_bf16 v[20:23], v[228:231], v[200:203], v[60:63]
	v_mfma_f32_16x16x32_bf16 v[128:131], v[224:227], v[28:31], v[68:71]
	v_mfma_f32_16x16x32_bf16 v[72:75], v[232:235], v[196:199], v[20:23]
	s_setprio 0
	s_barrier
	s_add_u32 s6, s64, 0x180
	ds_read_b128 v[40:43], v152 offset:49152
	ds_read_b128 v[48:51], v152 offset:50176
	ds_read_b128 v[196:199], v152 offset:51200
	ds_read_b128 v[200:203], v152 offset:52224
	ds_read_b128 v[236:239], v152 offset:53248
	ds_read_b128 v[240:243], v152 offset:54272
	ds_read_b128 v[244:247], v152 offset:55296
	ds_read_b128 v[248:251], v152 offset:56320
	s_addc_u32 s7, s65, 0
	s_add_i32 m0, s69, 0x18000
	s_nop 0
	global_load_lds_dwordx4 v1, s[6:7]
	s_nop 0
	s_add_i32 m0, s69, 0x1a000
	s_nop 0
	global_load_lds_dwordx4 v146, s[6:7]
	s_add_u32 s6, s64, 0x40180
	s_addc_u32 s7, s65, 0
	s_add_i32 m0, s69, 0x1c000
	s_nop 0
	global_load_lds_dwordx4 v1, s[6:7]
	s_nop 0
	s_add_i32 m0, s69, 0x1e000
	s_nop 0
	global_load_lds_dwordx4 v146, s[6:7]
	s_nop 0
	s_add_i32 m0, s69, 0x8000
	s_nop 0
	global_load_lds_dwordx4 v147, s[2:3]
	s_nop 0
	s_add_i32 m0, s69, 0xa000
	s_nop 0
	global_load_lds_dwordx4 v148, s[2:3]
	s_waitcnt vmcnt(8)
	s_waitcnt lgkmcnt(0)
	s_barrier
	s_setprio 1
	s_waitcnt lgkmcnt(7)
	v_mfma_f32_16x16x32_bf16 v[20:23], v[12:15], v[40:43], v[138:141]
	s_waitcnt lgkmcnt(6)
	v_mfma_f32_16x16x32_bf16 v[60:63], v[24:27], v[48:51], v[20:23]
	v_mfma_f32_16x16x32_bf16 v[20:23], v[32:35], v[40:43], v[142:145]
	v_mfma_f32_16x16x32_bf16 v[52:55], v[216:219], v[48:51], v[20:23]
	s_waitcnt lgkmcnt(5)
	v_mfma_f32_16x16x32_bf16 v[20:23], v[12:15], v[196:199], v[154:157]
	s_waitcnt lgkmcnt(4)
	v_mfma_f32_16x16x32_bf16 v[44:47], v[24:27], v[200:203], v[20:23]
	v_mfma_f32_16x16x32_bf16 v[20:23], v[32:35], v[196:199], v[158:161]
	v_mfma_f32_16x16x32_bf16 v[36:39], v[216:219], v[200:203], v[20:23]
	s_waitcnt lgkmcnt(3)
	v_mfma_f32_16x16x32_bf16 v[20:23], v[12:15], v[236:239], v[162:165]
	s_waitcnt lgkmcnt(1)
	v_mfma_f32_16x16x32_bf16 v[4:7], v[12:15], v[244:247], v[4:7]
	v_mfma_f32_16x16x32_bf16 v[28:31], v[24:27], v[240:243], v[20:23]
	v_mfma_f32_16x16x32_bf16 v[20:23], v[32:35], v[236:239], v[166:169]
	s_waitcnt lgkmcnt(0)
	v_mfma_f32_16x16x32_bf16 v[12:15], v[24:27], v[248:251], v[4:7]
	v_mfma_f32_16x16x32_bf16 v[4:7], v[32:35], v[244:247], v[8:11]
	v_mfma_f32_16x16x32_bf16 v[20:23], v[216:219], v[240:243], v[20:23]
	v_mfma_f32_16x16x32_bf16 v[4:7], v[216:219], v[248:251], v[4:7]
	s_setprio 0
	s_setprio 1
	v_mfma_f32_16x16x32_bf16 v[8:11], v[220:223], v[40:43], v[16:19]
	v_mfma_f32_16x16x32_bf16 v[68:71], v[224:227], v[48:51], v[8:11]
	v_mfma_f32_16x16x32_bf16 v[8:11], v[228:231], v[40:43], v[172:175]
	v_mfma_f32_16x16x32_bf16 v[56:59], v[232:235], v[48:51], v[8:11]
	v_mfma_f32_16x16x32_bf16 v[8:11], v[220:223], v[196:199], v[176:179]
	v_mfma_f32_16x16x32_bf16 v[48:51], v[224:227], v[200:203], v[8:11]
	v_mfma_f32_16x16x32_bf16 v[8:11], v[228:231], v[196:199], v[180:183]
	v_mfma_f32_16x16x32_bf16 v[40:43], v[232:235], v[200:203], v[8:11]
	v_mfma_f32_16x16x32_bf16 v[8:11], v[220:223], v[236:239], v[184:187]
	v_mfma_f32_16x16x32_bf16 v[32:35], v[224:227], v[240:243], v[8:11]
	v_mfma_f32_16x16x32_bf16 v[8:11], v[228:231], v[236:239], v[204:207]
	v_mfma_f32_16x16x32_bf16 v[24:27], v[232:235], v[240:243], v[8:11]
	v_mfma_f32_16x16x32_bf16 v[8:11], v[220:223], v[244:247], v[208:211]
	v_mfma_f32_16x16x32_bf16 v[16:19], v[224:227], v[248:251], v[8:11]
	v_mfma_f32_16x16x32_bf16 v[8:11], v[228:231], v[244:247], v[212:215]
	v_mfma_f32_16x16x32_bf16 v[8:11], v[232:235], v[248:251], v[8:11]
	s_setprio 0
	s_barrier
	s_add_i32 s2, s82, 1
	s_lshl_b32 s58, s82, 6
	s_and_b32 s3, s2, 31
	s_lshl_b32 s2, s2, 6
	s_add_i32 s59, s58, 0x9000
	s_add_i32 s52, s58, 0x8000
	s_add_i32 s40, s58, 0x7000
	s_addk_i32 s2, 0x6000
	s_cmp_eq_u32 s3, 0
	s_cselect_b32 s41, 0, 32
	s_cselect_b32 s50, 0, s2
	s_add_i32 s18, s58, 0x6000
	s_add_i32 s26, s58, 0x5000
	s_and_b32 s2, s82, 31
	s_add_i32 s3, s58, 0x4fc0
	s_cmp_eq_u32 s2, 0
	s_cselect_b32 s27, 0, 0x48
	s_cselect_b32 s6, 0, s3
	s_add_i32 s7, s58, 0x4000
	s_addk_i32 s58, 0x3000
	s_lshl_b64 s[2:3], s[82:83], 14
	s_add_u32 s84, s20, s2
	s_addc_u32 s85, s36, s3
	s_lshl_b32 s2, s82, 8
	s_and_b32 s2, s2, 0x400
	s_add_i32 s83, s2, 0
	s_add_i32 s83, s83, 0x24400

	.amdhsa_kernel _Z10fwd_kernel4Args
		.amdhsa_group_segment_fixed_size 0
		.amdhsa_private_segment_fixed_size 0
		.amdhsa_kernarg_size 416
		.amdhsa_user_sgpr_count 2
		.amdhsa_user_sgpr_dispatch_ptr 0
		.amdhsa_user_sgpr_queue_ptr 0
		.amdhsa_user_sgpr_kernarg_segment_ptr 1
		.amdhsa_user_sgpr_dispatch_id 0
		.amdhsa_user_sgpr_kernarg_preload_length 0
		.amdhsa_user_sgpr_kernarg_preload_offset 0
		.amdhsa_user_sgpr_private_segment_size 0
		.amdhsa_uses_dynamic_stack 0
		.amdhsa_enable_private_segment 0
		.amdhsa_system_sgpr_workgroup_id_x 1
		.amdhsa_system_sgpr_workgroup_id_y 0
		.amdhsa_system_sgpr_workgroup_id_z 0
		.amdhsa_system_sgpr_workgroup_info 0
		.amdhsa_system_vgpr_workitem_id 0
		.amdhsa_next_free_vgpr 256
		.amdhsa_next_free_sgpr 102
		.amdhsa_accum_offset 256
		.amdhsa_reserve_vcc 1
		.amdhsa_float_round_mode_32 0
		.amdhsa_float_round_mode_16_64 0
		.amdhsa_float_denorm_mode_32 3
		.amdhsa_float_denorm_mode_16_64 3
		.amdhsa_dx10_clamp 1
		.amdhsa_ieee_mode 1
		.amdhsa_fp16_overflow 0
		.amdhsa_tg_split 0
		.amdhsa_exception_fp_ieee_invalid_op 0
		.amdhsa_exception_fp_denorm_src 0
		.amdhsa_exception_fp_ieee_div_zero 0
		.amdhsa_exception_fp_ieee_overflow 0
		.amdhsa_exception_fp_ieee_underflow 0
		.amdhsa_exception_fp_ieee_inexact 0
		.amdhsa_exception_int_div_zero 0
	.end_amdhsa_kernel

amdhsa.kernels:
  - .agpr_count:     0
    .args:
      - .offset:         0
        .size:           160
        .value_kind:     by_value
      - .offset:         160
        .size:           4
        .value_kind:     hidden_block_count_x
      - .offset:         164
        .size:           4
        .value_kind:     hidden_block_count_y
      - .offset:         168
        .size:           4
        .value_kind:     hidden_block_count_z
      - .offset:         172
        .size:           2
        .value_kind:     hidden_group_size_x
      - .offset:         174
        .size:           2
        .value_kind:     hidden_group_size_y
      - .offset:         176
        .size:           2
        .value_kind:     hidden_group_size_z
      - .offset:         178
        .size:           2
        .value_kind:     hidden_remainder_x
      - .offset:         180
        .size:           2
        .value_kind:     hidden_remainder_y
      - .offset:         182
        .size:           2
        .value_kind:     hidden_remainder_z
      - .offset:         200
        .size:           8
        .value_kind:     hidden_global_offset_x
      - .offset:         208
        .size:           8
        .value_kind:     hidden_global_offset_y
      - .offset:         216
        .size:           8
        .value_kind:     hidden_global_offset_z
      - .offset:         224
        .size:           2
        .value_kind:     hidden_grid_dims
      - .offset:         280
        .size:           4
        .value_kind:     hidden_dynamic_lds_size
    .group_segment_fixed_size: 0
    .kernarg_segment_align: 8
    .kernarg_segment_size: 416
    .language:       OpenCL C
    .language_version:
      - 2
      - 0
    .max_flat_workgroup_size: 512
    .name:           _Z10fwd_kernel4Args
    .private_segment_fixed_size: 0
    .sgpr_count:     108
    .sgpr_spill_count: 22
    .symbol:         _Z10fwd_kernel4Args.kd
    .uniform_work_group_size: 1
    .uses_dynamic_stack: false
    .vgpr_count:     256
    .vgpr_spill_count: 0
    .wavefront_size: 64
